# phase-split k-loops on all seven GEMM loops, without the setprio pairs
# speedup vs baseline: 1.0392x; 1.0036x over previous
; #define GEMM_WAITV(n) asm volatile("s_waitcnt vmcnt(" #n ")" ::: "memory")
; template <bool SWAP>
; __device__ __forceinline__ void gemm_main(f32x4 (&acc)[8][4], const TP& t, int nk, char* lds) {
;     ...
; #pragma unroll 1
;   for (int kt = 0; kt < nk - 3; ++kt) {
;     GEMM_WAITV(8);
;     GEMM_STEP(kt, true)
;   }
.Lp2a_top:
	s_add_i32 s35, s34, 0xfffe8000
	s_and_b32 s35, s35, 0x18000
	v_add_u32_e32 v235, s35, v168
	v_add_u32_e32 v236, s35, v170
	ds_read_b128 v[184:187], v235
	ds_read_b128 v[156:159], v236 offset:16384
	ds_read_b128 v[172:175], v236 offset:17408
	ds_read_b128 v[176:179], v236 offset:18432
	ds_read_b128 v[180:183], v236 offset:19456
	ds_read_b128 v[188:191], v235 offset:1024
	ds_read_b128 v[192:195], v235 offset:2048
	ds_read_b128 v[198:201], v235 offset:3072
	s_and_b32 s99, s34, 0x18000
	s_add_i32 s99, s99, s98
	s_mov_b32 m0, s99
	s_nop 0
	global_load_lds_dwordx4 v[136:137], off
	s_add_i32 m0, s99, 0x400
	s_nop 0
	global_load_lds_dwordx4 v[138:139], off
	s_waitcnt lgkmcnt(0)
	s_barrier
	v_mfma_f32_16x16x32_bf16 v[124:127], v[184:187], v[156:159], v[124:127]
	v_mfma_f32_16x16x32_bf16 v[120:123], v[184:187], v[172:175], v[120:123]
	v_mfma_f32_16x16x32_bf16 v[116:119], v[184:187], v[176:179], v[116:119]
	v_mfma_f32_16x16x32_bf16 v[112:115], v[184:187], v[180:183], v[112:115]
	v_mfma_f32_16x16x32_bf16 v[108:111], v[188:191], v[156:159], v[108:111]
	v_mfma_f32_16x16x32_bf16 v[104:107], v[188:191], v[172:175], v[104:107]
	v_mfma_f32_16x16x32_bf16 v[100:103], v[188:191], v[176:179], v[100:103]
	v_mfma_f32_16x16x32_bf16 v[96:99], v[188:191], v[180:183], v[96:99]
	v_mfma_f32_16x16x32_bf16 v[92:95], v[192:195], v[156:159], v[92:95]
	v_mfma_f32_16x16x32_bf16 v[88:91], v[192:195], v[172:175], v[88:91]
	v_mfma_f32_16x16x32_bf16 v[84:87], v[192:195], v[176:179], v[84:87]
	v_mfma_f32_16x16x32_bf16 v[80:83], v[192:195], v[180:183], v[80:83]
	v_mfma_f32_16x16x32_bf16 v[76:79], v[198:201], v[156:159], v[76:79]
	v_mfma_f32_16x16x32_bf16 v[72:75], v[198:201], v[172:175], v[72:75]
	v_mfma_f32_16x16x32_bf16 v[68:71], v[198:201], v[176:179], v[68:71]
	v_mfma_f32_16x16x32_bf16 v[64:67], v[198:201], v[180:183], v[64:67]
	s_barrier
	ds_read_b128 v[184:187], v235 offset:4096
	ds_read_b128 v[188:191], v235 offset:5120
	ds_read_b128 v[192:195], v235 offset:6144
	ds_read_b128 v[198:201], v235 offset:7168
	s_add_i32 m0, s99, 0x4000
	s_nop 0
	global_load_lds_dwordx4 v[140:141], off
	s_add_i32 m0, s99, 0x4400
	s_nop 0
	global_load_lds_dwordx4 v[142:143], off
	v_lshl_add_u64 v[136:137], v[136:137], 0, 64
	v_lshl_add_u64 v[138:139], v[138:139], 0, 64
	v_lshl_add_u64 v[140:141], v[140:141], 0, 64
	v_lshl_add_u64 v[142:143], v[142:143], 0, 64
	s_add_i32 s34, s34, 0x8000
	s_waitcnt vmcnt(8)
	s_waitcnt lgkmcnt(0)
	s_barrier
	v_mfma_f32_16x16x32_bf16 v[60:63], v[184:187], v[156:159], v[60:63]
	v_mfma_f32_16x16x32_bf16 v[56:59], v[184:187], v[172:175], v[56:59]
	v_mfma_f32_16x16x32_bf16 v[52:55], v[184:187], v[176:179], v[52:55]
	v_mfma_f32_16x16x32_bf16 v[48:51], v[184:187], v[180:183], v[48:51]
	v_mfma_f32_16x16x32_bf16 v[44:47], v[188:191], v[156:159], v[44:47]
	v_mfma_f32_16x16x32_bf16 v[40:43], v[188:191], v[172:175], v[40:43]
	v_mfma_f32_16x16x32_bf16 v[36:39], v[188:191], v[176:179], v[36:39]
	v_mfma_f32_16x16x32_bf16 v[32:35], v[188:191], v[180:183], v[32:35]
	v_mfma_f32_16x16x32_bf16 v[28:31], v[192:195], v[156:159], v[28:31]
	v_mfma_f32_16x16x32_bf16 v[24:27], v[192:195], v[172:175], v[24:27]
	v_mfma_f32_16x16x32_bf16 v[20:23], v[192:195], v[176:179], v[20:23]
	v_mfma_f32_16x16x32_bf16 v[16:19], v[192:195], v[180:183], v[16:19]
	v_mfma_f32_16x16x32_bf16 v[12:15], v[198:201], v[156:159], v[12:15]
	v_mfma_f32_16x16x32_bf16 v[8:11], v[198:201], v[172:175], v[8:11]
	v_mfma_f32_16x16x32_bf16 v[4:7], v[198:201], v[176:179], v[4:7]
	v_mfma_f32_16x16x32_bf16 v[0:3], v[198:201], v[180:183], v[0:3]
	s_barrier
	s_cmp_lg_u32 s34, 0x100000
	s_cbranch_scc1 .Lp2a_top
	v_add_u32_e32 v235, 0x8000, v168
	v_add_u32_e32 v236, 0x8000, v170
	ds_read_b128 v[184:187], v235
	ds_read_b128 v[156:159], v236 offset:16384
	ds_read_b128 v[172:175], v236 offset:17408
	ds_read_b128 v[176:179], v236 offset:18432
	ds_read_b128 v[180:183], v236 offset:19456
	ds_read_b128 v[188:191], v235 offset:1024
	ds_read_b128 v[192:195], v235 offset:2048
	ds_read_b128 v[198:201], v235 offset:3072
	s_waitcnt lgkmcnt(0)
	s_barrier
	v_mfma_f32_16x16x32_bf16 v[124:127], v[184:187], v[156:159], v[124:127]
	v_mfma_f32_16x16x32_bf16 v[120:123], v[184:187], v[172:175], v[120:123]
	v_mfma_f32_16x16x32_bf16 v[116:119], v[184:187], v[176:179], v[116:119]
	v_mfma_f32_16x16x32_bf16 v[112:115], v[184:187], v[180:183], v[112:115]
	v_mfma_f32_16x16x32_bf16 v[108:111], v[188:191], v[156:159], v[108:111]
	v_mfma_f32_16x16x32_bf16 v[104:107], v[188:191], v[172:175], v[104:107]
	v_mfma_f32_16x16x32_bf16 v[100:103], v[188:191], v[176:179], v[100:103]
	v_mfma_f32_16x16x32_bf16 v[96:99], v[188:191], v[180:183], v[96:99]
	v_mfma_f32_16x16x32_bf16 v[92:95], v[192:195], v[156:159], v[92:95]
	v_mfma_f32_16x16x32_bf16 v[88:91], v[192:195], v[172:175], v[88:91]
	v_mfma_f32_16x16x32_bf16 v[84:87], v[192:195], v[176:179], v[84:87]
	v_mfma_f32_16x16x32_bf16 v[80:83], v[192:195], v[180:183], v[80:83]
	v_mfma_f32_16x16x32_bf16 v[76:79], v[198:201], v[156:159], v[76:79]
	v_mfma_f32_16x16x32_bf16 v[72:75], v[198:201], v[172:175], v[72:75]
	v_mfma_f32_16x16x32_bf16 v[68:71], v[198:201], v[176:179], v[68:71]
	v_mfma_f32_16x16x32_bf16 v[64:67], v[198:201], v[180:183], v[64:67]
	s_barrier
	ds_read_b128 v[184:187], v235 offset:4096
	ds_read_b128 v[188:191], v235 offset:5120
	ds_read_b128 v[192:195], v235 offset:6144
	ds_read_b128 v[198:201], v235 offset:7168
	s_waitcnt vmcnt(4)
	s_waitcnt lgkmcnt(0)
	s_barrier
; #define GEMM_WAITV(n) asm volatile("s_waitcnt vmcnt(" #n ")" ::: "memory")
; template <bool SWAP>
; __device__ __forceinline__ void gemm_main(f32x4 (&acc)[8][4], const TP& t, int nk, char* lds) {
;     ...
; #pragma unroll 1
;   for (int kt = nk - 3; kt < nk; ++kt) {
;     const int rem = nk - kt;
;     if (rem == 3) GEMM_WAITV(8); else if (rem == 2) GEMM_WAITV(4); else GEMM_WAITV(0);
;     GEMM_STEP(kt, false)
;   }
;   __builtin_amdgcn_s_barrier();
	v_mfma_f32_16x16x32_bf16 v[60:63], v[184:187], v[156:159], v[60:63]
	v_mfma_f32_16x16x32_bf16 v[56:59], v[184:187], v[172:175], v[56:59]
	v_mfma_f32_16x16x32_bf16 v[52:55], v[184:187], v[176:179], v[52:55]
	v_mfma_f32_16x16x32_bf16 v[48:51], v[184:187], v[180:183], v[48:51]
	v_mfma_f32_16x16x32_bf16 v[44:47], v[188:191], v[156:159], v[44:47]
	v_mfma_f32_16x16x32_bf16 v[40:43], v[188:191], v[172:175], v[40:43]
	v_mfma_f32_16x16x32_bf16 v[36:39], v[188:191], v[176:179], v[36:39]
	v_mfma_f32_16x16x32_bf16 v[32:35], v[188:191], v[180:183], v[32:35]
	v_mfma_f32_16x16x32_bf16 v[28:31], v[192:195], v[156:159], v[28:31]
	v_mfma_f32_16x16x32_bf16 v[24:27], v[192:195], v[172:175], v[24:27]
	v_mfma_f32_16x16x32_bf16 v[20:23], v[192:195], v[176:179], v[20:23]
	v_mfma_f32_16x16x32_bf16 v[16:19], v[192:195], v[180:183], v[16:19]
	v_mfma_f32_16x16x32_bf16 v[12:15], v[198:201], v[156:159], v[12:15]
	v_mfma_f32_16x16x32_bf16 v[8:11], v[198:201], v[172:175], v[8:11]
	v_mfma_f32_16x16x32_bf16 v[4:7], v[198:201], v[176:179], v[4:7]
	v_mfma_f32_16x16x32_bf16 v[0:3], v[198:201], v[180:183], v[0:3]
	s_barrier
	v_add_u32_e32 v235, 0x10000, v168
	v_add_u32_e32 v236, 0x10000, v170
	ds_read_b128 v[184:187], v235
	ds_read_b128 v[156:159], v236 offset:16384
	ds_read_b128 v[172:175], v236 offset:17408
	ds_read_b128 v[176:179], v236 offset:18432
	ds_read_b128 v[180:183], v236 offset:19456
	ds_read_b128 v[188:191], v235 offset:1024
	ds_read_b128 v[192:195], v235 offset:2048
	ds_read_b128 v[198:201], v235 offset:3072
	s_waitcnt lgkmcnt(0)
	s_barrier
	v_mfma_f32_16x16x32_bf16 v[124:127], v[184:187], v[156:159], v[124:127]
	v_mfma_f32_16x16x32_bf16 v[120:123], v[184:187], v[172:175], v[120:123]
	v_mfma_f32_16x16x32_bf16 v[116:119], v[184:187], v[176:179], v[116:119]
	v_mfma_f32_16x16x32_bf16 v[112:115], v[184:187], v[180:183], v[112:115]
	v_mfma_f32_16x16x32_bf16 v[108:111], v[188:191], v[156:159], v[108:111]
	v_mfma_f32_16x16x32_bf16 v[104:107], v[188:191], v[172:175], v[104:107]
	v_mfma_f32_16x16x32_bf16 v[100:103], v[188:191], v[176:179], v[100:103]
	v_mfma_f32_16x16x32_bf16 v[96:99], v[188:191], v[180:183], v[96:99]
	v_mfma_f32_16x16x32_bf16 v[92:95], v[192:195], v[156:159], v[92:95]
	v_mfma_f32_16x16x32_bf16 v[88:91], v[192:195], v[172:175], v[88:91]
	v_mfma_f32_16x16x32_bf16 v[84:87], v[192:195], v[176:179], v[84:87]
	v_mfma_f32_16x16x32_bf16 v[80:83], v[192:195], v[180:183], v[80:83]
	v_mfma_f32_16x16x32_bf16 v[76:79], v[198:201], v[156:159], v[76:79]
	v_mfma_f32_16x16x32_bf16 v[72:75], v[198:201], v[172:175], v[72:75]
	v_mfma_f32_16x16x32_bf16 v[68:71], v[198:201], v[176:179], v[68:71]
	v_mfma_f32_16x16x32_bf16 v[64:67], v[198:201], v[180:183], v[64:67]
	s_barrier
	ds_read_b128 v[184:187], v235 offset:4096
	ds_read_b128 v[188:191], v235 offset:5120
	ds_read_b128 v[192:195], v235 offset:6144
	ds_read_b128 v[198:201], v235 offset:7168
	s_waitcnt vmcnt(0)
	s_waitcnt lgkmcnt(0)
	s_barrier
	v_mfma_f32_16x16x32_bf16 v[60:63], v[184:187], v[156:159], v[60:63]
	v_mfma_f32_16x16x32_bf16 v[56:59], v[184:187], v[172:175], v[56:59]
	v_mfma_f32_16x16x32_bf16 v[52:55], v[184:187], v[176:179], v[52:55]
	v_mfma_f32_16x16x32_bf16 v[48:51], v[184:187], v[180:183], v[48:51]
	v_mfma_f32_16x16x32_bf16 v[44:47], v[188:191], v[156:159], v[44:47]
	v_mfma_f32_16x16x32_bf16 v[40:43], v[188:191], v[172:175], v[40:43]
	v_mfma_f32_16x16x32_bf16 v[36:39], v[188:191], v[176:179], v[36:39]
	v_mfma_f32_16x16x32_bf16 v[32:35], v[188:191], v[180:183], v[32:35]
	v_mfma_f32_16x16x32_bf16 v[28:31], v[192:195], v[156:159], v[28:31]
	v_mfma_f32_16x16x32_bf16 v[24:27], v[192:195], v[172:175], v[24:27]
	v_mfma_f32_16x16x32_bf16 v[20:23], v[192:195], v[176:179], v[20:23]
	v_mfma_f32_16x16x32_bf16 v[16:19], v[192:195], v[180:183], v[16:19]
	v_mfma_f32_16x16x32_bf16 v[12:15], v[198:201], v[156:159], v[12:15]
	v_mfma_f32_16x16x32_bf16 v[8:11], v[198:201], v[172:175], v[8:11]
	v_mfma_f32_16x16x32_bf16 v[4:7], v[198:201], v[176:179], v[4:7]
	v_mfma_f32_16x16x32_bf16 v[0:3], v[198:201], v[180:183], v[0:3]
	s_barrier
	v_add_u32_e32 v235, 0x18000, v168
	v_add_u32_e32 v236, 0x18000, v170
	ds_read_b128 v[184:187], v235
	ds_read_b128 v[156:159], v236 offset:16384
	ds_read_b128 v[172:175], v236 offset:17408
	ds_read_b128 v[176:179], v236 offset:18432
	ds_read_b128 v[180:183], v236 offset:19456
	ds_read_b128 v[188:191], v235 offset:1024
	ds_read_b128 v[192:195], v235 offset:2048
	ds_read_b128 v[198:201], v235 offset:3072
	s_waitcnt lgkmcnt(0)
	s_barrier
	v_mfma_f32_16x16x32_bf16 v[124:127], v[184:187], v[156:159], v[124:127]
	v_mfma_f32_16x16x32_bf16 v[120:123], v[184:187], v[172:175], v[120:123]
	v_mfma_f32_16x16x32_bf16 v[116:119], v[184:187], v[176:179], v[116:119]
	v_mfma_f32_16x16x32_bf16 v[112:115], v[184:187], v[180:183], v[112:115]
	v_mfma_f32_16x16x32_bf16 v[108:111], v[188:191], v[156:159], v[108:111]
	v_mfma_f32_16x16x32_bf16 v[104:107], v[188:191], v[172:175], v[104:107]
	v_mfma_f32_16x16x32_bf16 v[100:103], v[188:191], v[176:179], v[100:103]
	v_mfma_f32_16x16x32_bf16 v[96:99], v[188:191], v[180:183], v[96:99]
	v_mfma_f32_16x16x32_bf16 v[92:95], v[192:195], v[156:159], v[92:95]
	v_mfma_f32_16x16x32_bf16 v[88:91], v[192:195], v[172:175], v[88:91]
	v_mfma_f32_16x16x32_bf16 v[84:87], v[192:195], v[176:179], v[84:87]
	v_mfma_f32_16x16x32_bf16 v[80:83], v[192:195], v[180:183], v[80:83]
	v_mfma_f32_16x16x32_bf16 v[76:79], v[198:201], v[156:159], v[76:79]
	v_mfma_f32_16x16x32_bf16 v[72:75], v[198:201], v[172:175], v[72:75]
	v_mfma_f32_16x16x32_bf16 v[68:71], v[198:201], v[176:179], v[68:71]
	v_mfma_f32_16x16x32_bf16 v[64:67], v[198:201], v[180:183], v[64:67]
	s_barrier
	ds_read_b128 v[184:187], v235 offset:4096
	ds_read_b128 v[188:191], v235 offset:5120
	ds_read_b128 v[192:195], v235 offset:6144
	ds_read_b128 v[198:201], v235 offset:7168
	s_waitcnt lgkmcnt(0)
	s_barrier
	v_mfma_f32_16x16x32_bf16 v[60:63], v[184:187], v[156:159], v[60:63]
	v_mfma_f32_16x16x32_bf16 v[56:59], v[184:187], v[172:175], v[56:59]
	v_mfma_f32_16x16x32_bf16 v[52:55], v[184:187], v[176:179], v[52:55]
	v_mfma_f32_16x16x32_bf16 v[48:51], v[184:187], v[180:183], v[48:51]
	v_mfma_f32_16x16x32_bf16 v[44:47], v[188:191], v[156:159], v[44:47]
	v_mfma_f32_16x16x32_bf16 v[40:43], v[188:191], v[172:175], v[40:43]
	v_mfma_f32_16x16x32_bf16 v[36:39], v[188:191], v[176:179], v[36:39]
	v_mfma_f32_16x16x32_bf16 v[32:35], v[188:191], v[180:183], v[32:35]
	v_mfma_f32_16x16x32_bf16 v[28:31], v[192:195], v[156:159], v[28:31]
	v_mfma_f32_16x16x32_bf16 v[24:27], v[192:195], v[172:175], v[24:27]
	v_mfma_f32_16x16x32_bf16 v[20:23], v[192:195], v[176:179], v[20:23]
	v_mfma_f32_16x16x32_bf16 v[16:19], v[192:195], v[180:183], v[16:19]
	v_mfma_f32_16x16x32_bf16 v[12:15], v[198:201], v[156:159], v[12:15]
	v_mfma_f32_16x16x32_bf16 v[8:11], v[198:201], v[172:175], v[8:11]
	v_mfma_f32_16x16x32_bf16 v[4:7], v[198:201], v[176:179], v[4:7]
	v_mfma_f32_16x16x32_bf16 v[0:3], v[198:201], v[180:183], v[0:3]
	s_barrier
	s_cmp_ge_u32 s98, 0x2000
	s_cbranch_scc1 .Lp2a_done
	s_barrier

; #define GEMM_WAITV(n) asm volatile("s_waitcnt vmcnt(" #n ")" ::: "memory")
; template <bool SWAP>
; __device__ __forceinline__ void gemm_main(f32x4 (&acc)[8][4], const TP& t, int nk, char* lds) {
;     ...
; #pragma unroll 1
;   for (int kt = 0; kt < nk - 3; ++kt) {
;     GEMM_WAITV(8);
;     GEMM_STEP(kt, true)
;   }
.Lp2b_top:
	s_add_i32 s35, s34, 0xfffe8000
	s_and_b32 s35, s35, 0x18000
	v_add_u32_e32 v235, s35, v140
	v_add_u32_e32 v236, s35, v141
	ds_read_b128 v[178:181], v235
	ds_read_b128 v[156:159], v236 offset:16384
	ds_read_b128 v[164:167], v236 offset:17408
	ds_read_b128 v[170:173], v236 offset:18432
	ds_read_b128 v[174:177], v236 offset:19456
	ds_read_b128 v[182:185], v235 offset:1024
	ds_read_b128 v[186:189], v235 offset:2048
	ds_read_b128 v[190:193], v235 offset:3072
	s_and_b32 s99, s34, 0x18000
	s_add_i32 s99, s99, s98
	s_mov_b32 m0, s99
	s_nop 0
	global_load_lds_dwordx4 v[128:129], off
	s_add_i32 m0, s99, 0x400
	s_nop 0
	global_load_lds_dwordx4 v[130:131], off
	s_waitcnt lgkmcnt(0)
	s_barrier
	v_mfma_f32_16x16x32_bf16 v[124:127], v[156:159], v[178:181], v[124:127]
	v_mfma_f32_16x16x32_bf16 v[120:123], v[164:167], v[178:181], v[120:123]
	v_mfma_f32_16x16x32_bf16 v[116:119], v[170:173], v[178:181], v[116:119]
	v_mfma_f32_16x16x32_bf16 v[112:115], v[174:177], v[178:181], v[112:115]
	v_mfma_f32_16x16x32_bf16 v[108:111], v[156:159], v[182:185], v[108:111]
	v_mfma_f32_16x16x32_bf16 v[104:107], v[164:167], v[182:185], v[104:107]
	v_mfma_f32_16x16x32_bf16 v[100:103], v[170:173], v[182:185], v[100:103]
	v_mfma_f32_16x16x32_bf16 v[96:99], v[174:177], v[182:185], v[96:99]
	v_mfma_f32_16x16x32_bf16 v[92:95], v[156:159], v[186:189], v[92:95]
	v_mfma_f32_16x16x32_bf16 v[88:91], v[164:167], v[186:189], v[88:91]
	v_mfma_f32_16x16x32_bf16 v[84:87], v[170:173], v[186:189], v[84:87]
	v_mfma_f32_16x16x32_bf16 v[80:83], v[174:177], v[186:189], v[80:83]
	v_mfma_f32_16x16x32_bf16 v[76:79], v[156:159], v[190:193], v[76:79]
	v_mfma_f32_16x16x32_bf16 v[72:75], v[164:167], v[190:193], v[72:75]
	v_mfma_f32_16x16x32_bf16 v[68:71], v[170:173], v[190:193], v[68:71]
	v_mfma_f32_16x16x32_bf16 v[64:67], v[174:177], v[190:193], v[64:67]
	s_barrier
	ds_read_b128 v[178:181], v235 offset:4096
	ds_read_b128 v[182:185], v235 offset:5120
	ds_read_b128 v[186:189], v235 offset:6144
	ds_read_b128 v[190:193], v235 offset:7168
	s_add_i32 m0, s99, 0x4000
	s_nop 0
	global_load_lds_dwordx4 v[132:133], off
	s_add_i32 m0, s99, 0x4400
	s_nop 0
	global_load_lds_dwordx4 v[134:135], off
	v_lshl_add_u64 v[128:129], v[128:129], 0, 64
	v_lshl_add_u64 v[130:131], v[130:131], 0, 64
	v_lshl_add_u64 v[132:133], v[132:133], 0, 64
	v_lshl_add_u64 v[134:135], v[134:135], 0, 64
	s_add_i32 s34, s34, 0x8000
	s_waitcnt vmcnt(8)
	s_waitcnt lgkmcnt(0)
	s_barrier
	v_mfma_f32_16x16x32_bf16 v[60:63], v[156:159], v[178:181], v[60:63]
	v_mfma_f32_16x16x32_bf16 v[56:59], v[164:167], v[178:181], v[56:59]
	v_mfma_f32_16x16x32_bf16 v[52:55], v[170:173], v[178:181], v[52:55]
	v_mfma_f32_16x16x32_bf16 v[48:51], v[174:177], v[178:181], v[48:51]
	v_mfma_f32_16x16x32_bf16 v[44:47], v[156:159], v[182:185], v[44:47]
	v_mfma_f32_16x16x32_bf16 v[40:43], v[164:167], v[182:185], v[40:43]
	v_mfma_f32_16x16x32_bf16 v[36:39], v[170:173], v[182:185], v[36:39]
	v_mfma_f32_16x16x32_bf16 v[32:35], v[174:177], v[182:185], v[32:35]
	v_mfma_f32_16x16x32_bf16 v[28:31], v[156:159], v[186:189], v[28:31]
	v_mfma_f32_16x16x32_bf16 v[24:27], v[164:167], v[186:189], v[24:27]
	v_mfma_f32_16x16x32_bf16 v[20:23], v[170:173], v[186:189], v[20:23]
	v_mfma_f32_16x16x32_bf16 v[16:19], v[174:177], v[186:189], v[16:19]
	v_mfma_f32_16x16x32_bf16 v[12:15], v[156:159], v[190:193], v[12:15]
	v_mfma_f32_16x16x32_bf16 v[8:11], v[164:167], v[190:193], v[8:11]
	v_mfma_f32_16x16x32_bf16 v[4:7], v[170:173], v[190:193], v[4:7]
	v_mfma_f32_16x16x32_bf16 v[0:3], v[174:177], v[190:193], v[0:3]
	s_barrier
	s_cmp_lg_u32 s34, 0x100000
	s_cbranch_scc1 .Lp2b_top
	v_add_u32_e32 v235, 0x8000, v140
	v_add_u32_e32 v236, 0x8000, v141
	ds_read_b128 v[178:181], v235
	ds_read_b128 v[156:159], v236 offset:16384
	ds_read_b128 v[164:167], v236 offset:17408
	ds_read_b128 v[170:173], v236 offset:18432
	ds_read_b128 v[174:177], v236 offset:19456
	ds_read_b128 v[182:185], v235 offset:1024
	ds_read_b128 v[186:189], v235 offset:2048
	ds_read_b128 v[190:193], v235 offset:3072
	s_waitcnt lgkmcnt(0)
	s_barrier
	v_mfma_f32_16x16x32_bf16 v[124:127], v[156:159], v[178:181], v[124:127]
	v_mfma_f32_16x16x32_bf16 v[120:123], v[164:167], v[178:181], v[120:123]
	v_mfma_f32_16x16x32_bf16 v[116:119], v[170:173], v[178:181], v[116:119]
	v_mfma_f32_16x16x32_bf16 v[112:115], v[174:177], v[178:181], v[112:115]
	v_mfma_f32_16x16x32_bf16 v[108:111], v[156:159], v[182:185], v[108:111]
	v_mfma_f32_16x16x32_bf16 v[104:107], v[164:167], v[182:185], v[104:107]
	v_mfma_f32_16x16x32_bf16 v[100:103], v[170:173], v[182:185], v[100:103]
	v_mfma_f32_16x16x32_bf16 v[96:99], v[174:177], v[182:185], v[96:99]
	v_mfma_f32_16x16x32_bf16 v[92:95], v[156:159], v[186:189], v[92:95]
	v_mfma_f32_16x16x32_bf16 v[88:91], v[164:167], v[186:189], v[88:91]
	v_mfma_f32_16x16x32_bf16 v[84:87], v[170:173], v[186:189], v[84:87]
	v_mfma_f32_16x16x32_bf16 v[80:83], v[174:177], v[186:189], v[80:83]
	v_mfma_f32_16x16x32_bf16 v[76:79], v[156:159], v[190:193], v[76:79]
	v_mfma_f32_16x16x32_bf16 v[72:75], v[164:167], v[190:193], v[72:75]
	v_mfma_f32_16x16x32_bf16 v[68:71], v[170:173], v[190:193], v[68:71]
	v_mfma_f32_16x16x32_bf16 v[64:67], v[174:177], v[190:193], v[64:67]
	s_barrier
	ds_read_b128 v[178:181], v235 offset:4096
	ds_read_b128 v[182:185], v235 offset:5120
	ds_read_b128 v[186:189], v235 offset:6144
	ds_read_b128 v[190:193], v235 offset:7168
	s_waitcnt vmcnt(4)
	s_waitcnt lgkmcnt(0)
	s_barrier
; #define GEMM_WAITV(n) asm volatile("s_waitcnt vmcnt(" #n ")" ::: "memory")
; template <bool SWAP>
; __device__ __forceinline__ void gemm_main(f32x4 (&acc)[8][4], const TP& t, int nk, char* lds) {
;     ...
; #pragma unroll 1
;   for (int kt = nk - 3; kt < nk; ++kt) {
;     const int rem = nk - kt;
;     if (rem == 3) GEMM_WAITV(8); else if (rem == 2) GEMM_WAITV(4); else GEMM_WAITV(0);
;     GEMM_STEP(kt, false)
;   }
;   __builtin_amdgcn_s_barrier();
	v_mfma_f32_16x16x32_bf16 v[60:63], v[156:159], v[178:181], v[60:63]
	v_mfma_f32_16x16x32_bf16 v[56:59], v[164:167], v[178:181], v[56:59]
	v_mfma_f32_16x16x32_bf16 v[52:55], v[170:173], v[178:181], v[52:55]
	v_mfma_f32_16x16x32_bf16 v[48:51], v[174:177], v[178:181], v[48:51]
	v_mfma_f32_16x16x32_bf16 v[44:47], v[156:159], v[182:185], v[44:47]
	v_mfma_f32_16x16x32_bf16 v[40:43], v[164:167], v[182:185], v[40:43]
	v_mfma_f32_16x16x32_bf16 v[36:39], v[170:173], v[182:185], v[36:39]
	v_mfma_f32_16x16x32_bf16 v[32:35], v[174:177], v[182:185], v[32:35]
	v_mfma_f32_16x16x32_bf16 v[28:31], v[156:159], v[186:189], v[28:31]
	v_mfma_f32_16x16x32_bf16 v[24:27], v[164:167], v[186:189], v[24:27]
	v_mfma_f32_16x16x32_bf16 v[20:23], v[170:173], v[186:189], v[20:23]
	v_mfma_f32_16x16x32_bf16 v[16:19], v[174:177], v[186:189], v[16:19]
	v_mfma_f32_16x16x32_bf16 v[12:15], v[156:159], v[190:193], v[12:15]
	v_mfma_f32_16x16x32_bf16 v[8:11], v[164:167], v[190:193], v[8:11]
	v_mfma_f32_16x16x32_bf16 v[4:7], v[170:173], v[190:193], v[4:7]
	v_mfma_f32_16x16x32_bf16 v[0:3], v[174:177], v[190:193], v[0:3]
	s_barrier
	v_add_u32_e32 v235, 0x10000, v140
	v_add_u32_e32 v236, 0x10000, v141
	ds_read_b128 v[178:181], v235
	ds_read_b128 v[156:159], v236 offset:16384
	ds_read_b128 v[164:167], v236 offset:17408
	ds_read_b128 v[170:173], v236 offset:18432
	ds_read_b128 v[174:177], v236 offset:19456
	ds_read_b128 v[182:185], v235 offset:1024
	ds_read_b128 v[186:189], v235 offset:2048
	ds_read_b128 v[190:193], v235 offset:3072
	s_waitcnt lgkmcnt(0)
	s_barrier
	v_mfma_f32_16x16x32_bf16 v[124:127], v[156:159], v[178:181], v[124:127]
	v_mfma_f32_16x16x32_bf16 v[120:123], v[164:167], v[178:181], v[120:123]
	v_mfma_f32_16x16x32_bf16 v[116:119], v[170:173], v[178:181], v[116:119]
	v_mfma_f32_16x16x32_bf16 v[112:115], v[174:177], v[178:181], v[112:115]
	v_mfma_f32_16x16x32_bf16 v[108:111], v[156:159], v[182:185], v[108:111]
	v_mfma_f32_16x16x32_bf16 v[104:107], v[164:167], v[182:185], v[104:107]
	v_mfma_f32_16x16x32_bf16 v[100:103], v[170:173], v[182:185], v[100:103]
	v_mfma_f32_16x16x32_bf16 v[96:99], v[174:177], v[182:185], v[96:99]
	v_mfma_f32_16x16x32_bf16 v[92:95], v[156:159], v[186:189], v[92:95]
	v_mfma_f32_16x16x32_bf16 v[88:91], v[164:167], v[186:189], v[88:91]
	v_mfma_f32_16x16x32_bf16 v[84:87], v[170:173], v[186:189], v[84:87]
	v_mfma_f32_16x16x32_bf16 v[80:83], v[174:177], v[186:189], v[80:83]
	v_mfma_f32_16x16x32_bf16 v[76:79], v[156:159], v[190:193], v[76:79]
	v_mfma_f32_16x16x32_bf16 v[72:75], v[164:167], v[190:193], v[72:75]
	v_mfma_f32_16x16x32_bf16 v[68:71], v[170:173], v[190:193], v[68:71]
	v_mfma_f32_16x16x32_bf16 v[64:67], v[174:177], v[190:193], v[64:67]
	s_barrier
	ds_read_b128 v[178:181], v235 offset:4096
	ds_read_b128 v[182:185], v235 offset:5120
	ds_read_b128 v[186:189], v235 offset:6144
	ds_read_b128 v[190:193], v235 offset:7168
	s_waitcnt vmcnt(0)
	s_waitcnt lgkmcnt(0)
	s_barrier
	v_mfma_f32_16x16x32_bf16 v[60:63], v[156:159], v[178:181], v[60:63]
	v_mfma_f32_16x16x32_bf16 v[56:59], v[164:167], v[178:181], v[56:59]
	v_mfma_f32_16x16x32_bf16 v[52:55], v[170:173], v[178:181], v[52:55]
	v_mfma_f32_16x16x32_bf16 v[48:51], v[174:177], v[178:181], v[48:51]
	v_mfma_f32_16x16x32_bf16 v[44:47], v[156:159], v[182:185], v[44:47]
	v_mfma_f32_16x16x32_bf16 v[40:43], v[164:167], v[182:185], v[40:43]
	v_mfma_f32_16x16x32_bf16 v[36:39], v[170:173], v[182:185], v[36:39]
	v_mfma_f32_16x16x32_bf16 v[32:35], v[174:177], v[182:185], v[32:35]
	v_mfma_f32_16x16x32_bf16 v[28:31], v[156:159], v[186:189], v[28:31]
	v_mfma_f32_16x16x32_bf16 v[24:27], v[164:167], v[186:189], v[24:27]
	v_mfma_f32_16x16x32_bf16 v[20:23], v[170:173], v[186:189], v[20:23]
	v_mfma_f32_16x16x32_bf16 v[16:19], v[174:177], v[186:189], v[16:19]
	v_mfma_f32_16x16x32_bf16 v[12:15], v[156:159], v[190:193], v[12:15]
	v_mfma_f32_16x16x32_bf16 v[8:11], v[164:167], v[190:193], v[8:11]
	v_mfma_f32_16x16x32_bf16 v[4:7], v[170:173], v[190:193], v[4:7]
	v_mfma_f32_16x16x32_bf16 v[0:3], v[174:177], v[190:193], v[0:3]
	s_barrier
	v_add_u32_e32 v235, 0x18000, v140
	v_add_u32_e32 v236, 0x18000, v141
	ds_read_b128 v[178:181], v235
	ds_read_b128 v[156:159], v236 offset:16384
	ds_read_b128 v[164:167], v236 offset:17408
	ds_read_b128 v[170:173], v236 offset:18432
	ds_read_b128 v[174:177], v236 offset:19456
	ds_read_b128 v[182:185], v235 offset:1024
	ds_read_b128 v[186:189], v235 offset:2048
	ds_read_b128 v[190:193], v235 offset:3072
	s_waitcnt lgkmcnt(0)
	s_barrier
	v_mfma_f32_16x16x32_bf16 v[124:127], v[156:159], v[178:181], v[124:127]
	v_mfma_f32_16x16x32_bf16 v[120:123], v[164:167], v[178:181], v[120:123]
	v_mfma_f32_16x16x32_bf16 v[116:119], v[170:173], v[178:181], v[116:119]
	v_mfma_f32_16x16x32_bf16 v[112:115], v[174:177], v[178:181], v[112:115]
	v_mfma_f32_16x16x32_bf16 v[108:111], v[156:159], v[182:185], v[108:111]
	v_mfma_f32_16x16x32_bf16 v[104:107], v[164:167], v[182:185], v[104:107]
	v_mfma_f32_16x16x32_bf16 v[100:103], v[170:173], v[182:185], v[100:103]
	v_mfma_f32_16x16x32_bf16 v[96:99], v[174:177], v[182:185], v[96:99]
	v_mfma_f32_16x16x32_bf16 v[92:95], v[156:159], v[186:189], v[92:95]
	v_mfma_f32_16x16x32_bf16 v[88:91], v[164:167], v[186:189], v[88:91]
	v_mfma_f32_16x16x32_bf16 v[84:87], v[170:173], v[186:189], v[84:87]
	v_mfma_f32_16x16x32_bf16 v[80:83], v[174:177], v[186:189], v[80:83]
	v_mfma_f32_16x16x32_bf16 v[76:79], v[156:159], v[190:193], v[76:79]
	v_mfma_f32_16x16x32_bf16 v[72:75], v[164:167], v[190:193], v[72:75]
	v_mfma_f32_16x16x32_bf16 v[68:71], v[170:173], v[190:193], v[68:71]
	v_mfma_f32_16x16x32_bf16 v[64:67], v[174:177], v[190:193], v[64:67]
	s_barrier
	ds_read_b128 v[178:181], v235 offset:4096
	ds_read_b128 v[182:185], v235 offset:5120
	ds_read_b128 v[186:189], v235 offset:6144
	ds_read_b128 v[190:193], v235 offset:7168
	s_waitcnt lgkmcnt(0)
	s_barrier
	v_mfma_f32_16x16x32_bf16 v[60:63], v[156:159], v[178:181], v[60:63]
	v_mfma_f32_16x16x32_bf16 v[56:59], v[164:167], v[178:181], v[56:59]
	v_mfma_f32_16x16x32_bf16 v[52:55], v[170:173], v[178:181], v[52:55]
	v_mfma_f32_16x16x32_bf16 v[48:51], v[174:177], v[178:181], v[48:51]
	v_mfma_f32_16x16x32_bf16 v[44:47], v[156:159], v[182:185], v[44:47]
	v_mfma_f32_16x16x32_bf16 v[40:43], v[164:167], v[182:185], v[40:43]
	v_mfma_f32_16x16x32_bf16 v[36:39], v[170:173], v[182:185], v[36:39]
	v_mfma_f32_16x16x32_bf16 v[32:35], v[174:177], v[182:185], v[32:35]
	v_mfma_f32_16x16x32_bf16 v[28:31], v[156:159], v[186:189], v[28:31]
	v_mfma_f32_16x16x32_bf16 v[24:27], v[164:167], v[186:189], v[24:27]
	v_mfma_f32_16x16x32_bf16 v[20:23], v[170:173], v[186:189], v[20:23]
	v_mfma_f32_16x16x32_bf16 v[16:19], v[174:177], v[186:189], v[16:19]
	v_mfma_f32_16x16x32_bf16 v[12:15], v[156:159], v[190:193], v[12:15]
	v_mfma_f32_16x16x32_bf16 v[8:11], v[164:167], v[190:193], v[8:11]
	v_mfma_f32_16x16x32_bf16 v[4:7], v[170:173], v[190:193], v[4:7]
	v_mfma_f32_16x16x32_bf16 v[0:3], v[174:177], v[190:193], v[0:3]
	s_barrier
	s_cmp_ge_u32 s98, 0x2000
	s_cbranch_scc1 .Lp2b_done
	s_barrier

; #define GEMM_WAITV(n) asm volatile("s_waitcnt vmcnt(" #n ")" ::: "memory")
; template <bool SWAP>
; __device__ __forceinline__ void gemm_main(f32x4 (&acc)[8][4], const TP& t, int nk, char* lds) {
;     ...
; #pragma unroll 1
;   for (int kt = 0; kt < nk - 3; ++kt) {
;     GEMM_WAITV(8);
;     GEMM_STEP(kt, true)
;   }
; __device__ __forceinline__ void merge_phase(const Params& p, int first, int step, int n, char* lds) {
;     ...
;     gemm_main<true>(acc, cur, 16, lds);
.Lmg1_top:
	s_add_i32 s47, s46, 0xfffe8000
	s_and_b32 s47, s47, 0x18000
	v_add_u32_e32 v235, s47, v140
	v_add_u32_e32 v236, s47, v141
	ds_read_b128 v[174:177], v235
	ds_read_b128 v[144:147], v236 offset:16384
	ds_read_b128 v[158:161], v236 offset:17408
	ds_read_b128 v[162:165], v236 offset:18432
	ds_read_b128 v[170:173], v236 offset:19456
	ds_read_b128 v[178:181], v235 offset:1024
	ds_read_b128 v[182:185], v235 offset:2048
	ds_read_b128 v[186:189], v235 offset:3072
	s_and_b32 s99, s46, 0x18000
	s_add_i32 s99, s99, s98
	s_mov_b32 m0, s99
	s_nop 0
	global_load_lds_dwordx4 v[128:129], off
	s_add_i32 m0, s99, 0x400
	s_nop 0
	global_load_lds_dwordx4 v[130:131], off
	s_waitcnt lgkmcnt(0)
	s_barrier
	v_mfma_f32_16x16x32_bf16 v[0:3], v[144:147], v[174:177], v[0:3]
	v_mfma_f32_16x16x32_bf16 v[4:7], v[158:161], v[174:177], v[4:7]
	v_mfma_f32_16x16x32_bf16 v[16:19], v[162:165], v[174:177], v[16:19]
	v_mfma_f32_16x16x32_bf16 v[12:15], v[170:173], v[174:177], v[12:15]
	v_mfma_f32_16x16x32_bf16 v[20:23], v[144:147], v[178:181], v[20:23]
	v_mfma_f32_16x16x32_bf16 v[28:31], v[158:161], v[178:181], v[28:31]
	v_mfma_f32_16x16x32_bf16 v[48:51], v[162:165], v[178:181], v[48:51]
	v_mfma_f32_16x16x32_bf16 v[40:43], v[170:173], v[178:181], v[40:43]
	v_mfma_f32_16x16x32_bf16 v[52:55], v[144:147], v[182:185], v[52:55]
	v_mfma_f32_16x16x32_bf16 v[56:59], v[158:161], v[182:185], v[56:59]
	v_mfma_f32_16x16x32_bf16 v[72:75], v[162:165], v[182:185], v[72:75]
	v_mfma_f32_16x16x32_bf16 v[68:71], v[170:173], v[182:185], v[68:71]
	v_mfma_f32_16x16x32_bf16 v[76:79], v[144:147], v[186:189], v[76:79]
	v_mfma_f32_16x16x32_bf16 v[80:83], v[158:161], v[186:189], v[80:83]
	v_mfma_f32_16x16x32_bf16 v[100:103], v[162:165], v[186:189], v[100:103]
	v_mfma_f32_16x16x32_bf16 v[96:99], v[170:173], v[186:189], v[96:99]
	s_barrier
	ds_read_b128 v[174:177], v235 offset:4096
	ds_read_b128 v[178:181], v235 offset:5120
	ds_read_b128 v[182:185], v235 offset:6144
	ds_read_b128 v[186:189], v235 offset:7168
	s_add_i32 m0, s99, 0x4000
	s_nop 0
	global_load_lds_dwordx4 v[132:133], off
	s_add_i32 m0, s99, 0x4400
	s_nop 0
	global_load_lds_dwordx4 v[134:135], off
	v_lshl_add_u64 v[128:129], v[128:129], 0, 64
	v_lshl_add_u64 v[130:131], v[130:131], 0, 64
	v_lshl_add_u64 v[132:133], v[132:133], 0, 64
	v_lshl_add_u64 v[134:135], v[134:135], 0, 64
	s_add_i32 s46, s46, 0x8000
	s_waitcnt vmcnt(8)
	s_waitcnt lgkmcnt(0)
	s_barrier
	v_mfma_f32_16x16x32_bf16 v[104:107], v[144:147], v[174:177], v[104:107]
	v_mfma_f32_16x16x32_bf16 v[108:111], v[158:161], v[174:177], v[108:111]
	v_mfma_f32_16x16x32_bf16 v[120:123], v[162:165], v[174:177], v[120:123]
	v_mfma_f32_16x16x32_bf16 v[116:119], v[170:173], v[174:177], v[116:119]
	v_mfma_f32_16x16x32_bf16 v[124:127], v[144:147], v[178:181], v[124:127]
	v_mfma_f32_16x16x32_bf16 v[112:115], v[158:161], v[178:181], v[112:115]
	v_mfma_f32_16x16x32_bf16 v[92:95], v[162:165], v[178:181], v[92:95]
	v_mfma_f32_16x16x32_bf16 v[88:91], v[170:173], v[178:181], v[88:91]
	v_mfma_f32_16x16x32_bf16 v[84:87], v[144:147], v[182:185], v[84:87]
	v_mfma_f32_16x16x32_bf16 v[64:67], v[158:161], v[182:185], v[64:67]
	v_mfma_f32_16x16x32_bf16 v[60:63], v[162:165], v[182:185], v[60:63]
	v_mfma_f32_16x16x32_bf16 v[44:47], v[170:173], v[182:185], v[44:47]
	v_mfma_f32_16x16x32_bf16 v[36:39], v[144:147], v[186:189], v[36:39]
	v_mfma_f32_16x16x32_bf16 v[32:35], v[158:161], v[186:189], v[32:35]
	v_mfma_f32_16x16x32_bf16 v[24:27], v[162:165], v[186:189], v[24:27]
	v_mfma_f32_16x16x32_bf16 v[8:11], v[170:173], v[186:189], v[8:11]
	s_barrier
	s_cmp_lg_u32 s46, 0x80000
	s_cbranch_scc1 .Lmg1_top
	v_add_u32_e32 v235, 0x8000, v140
	v_add_u32_e32 v236, 0x8000, v141
	ds_read_b128 v[174:177], v235
	ds_read_b128 v[144:147], v236 offset:16384
	ds_read_b128 v[158:161], v236 offset:17408
	ds_read_b128 v[162:165], v236 offset:18432
	ds_read_b128 v[170:173], v236 offset:19456
	ds_read_b128 v[178:181], v235 offset:1024
	ds_read_b128 v[182:185], v235 offset:2048
	ds_read_b128 v[186:189], v235 offset:3072
	s_waitcnt lgkmcnt(0)
	s_barrier
	v_mfma_f32_16x16x32_bf16 v[0:3], v[144:147], v[174:177], v[0:3]
	v_mfma_f32_16x16x32_bf16 v[4:7], v[158:161], v[174:177], v[4:7]
	v_mfma_f32_16x16x32_bf16 v[16:19], v[162:165], v[174:177], v[16:19]
	v_mfma_f32_16x16x32_bf16 v[12:15], v[170:173], v[174:177], v[12:15]
	v_mfma_f32_16x16x32_bf16 v[20:23], v[144:147], v[178:181], v[20:23]
	v_mfma_f32_16x16x32_bf16 v[28:31], v[158:161], v[178:181], v[28:31]
	v_mfma_f32_16x16x32_bf16 v[48:51], v[162:165], v[178:181], v[48:51]
	v_mfma_f32_16x16x32_bf16 v[40:43], v[170:173], v[178:181], v[40:43]
	v_mfma_f32_16x16x32_bf16 v[52:55], v[144:147], v[182:185], v[52:55]
	v_mfma_f32_16x16x32_bf16 v[56:59], v[158:161], v[182:185], v[56:59]
	v_mfma_f32_16x16x32_bf16 v[72:75], v[162:165], v[182:185], v[72:75]
	v_mfma_f32_16x16x32_bf16 v[68:71], v[170:173], v[182:185], v[68:71]
	v_mfma_f32_16x16x32_bf16 v[76:79], v[144:147], v[186:189], v[76:79]
	v_mfma_f32_16x16x32_bf16 v[80:83], v[158:161], v[186:189], v[80:83]
	v_mfma_f32_16x16x32_bf16 v[100:103], v[162:165], v[186:189], v[100:103]
	v_mfma_f32_16x16x32_bf16 v[96:99], v[170:173], v[186:189], v[96:99]
	s_barrier
	ds_read_b128 v[174:177], v235 offset:4096
	ds_read_b128 v[178:181], v235 offset:5120
	ds_read_b128 v[182:185], v235 offset:6144
	ds_read_b128 v[186:189], v235 offset:7168
	s_waitcnt vmcnt(4)
	s_waitcnt lgkmcnt(0)
	s_barrier
; #define GEMM_WAITV(n) asm volatile("s_waitcnt vmcnt(" #n ")" ::: "memory")
; template <bool SWAP>
; __device__ __forceinline__ void gemm_main(f32x4 (&acc)[8][4], const TP& t, int nk, char* lds) {
;     ...
; #pragma unroll 1
;   for (int kt = nk - 3; kt < nk; ++kt) {
;     const int rem = nk - kt;
;     if (rem == 3) GEMM_WAITV(8); else if (rem == 2) GEMM_WAITV(4); else GEMM_WAITV(0);
;     GEMM_STEP(kt, false)
;   }
;   __builtin_amdgcn_s_barrier();
	v_mfma_f32_16x16x32_bf16 v[104:107], v[144:147], v[174:177], v[104:107]
	v_mfma_f32_16x16x32_bf16 v[108:111], v[158:161], v[174:177], v[108:111]
	v_mfma_f32_16x16x32_bf16 v[120:123], v[162:165], v[174:177], v[120:123]
	v_mfma_f32_16x16x32_bf16 v[116:119], v[170:173], v[174:177], v[116:119]
	v_mfma_f32_16x16x32_bf16 v[124:127], v[144:147], v[178:181], v[124:127]
	v_mfma_f32_16x16x32_bf16 v[112:115], v[158:161], v[178:181], v[112:115]
	v_mfma_f32_16x16x32_bf16 v[92:95], v[162:165], v[178:181], v[92:95]
	v_mfma_f32_16x16x32_bf16 v[88:91], v[170:173], v[178:181], v[88:91]
	v_mfma_f32_16x16x32_bf16 v[84:87], v[144:147], v[182:185], v[84:87]
	v_mfma_f32_16x16x32_bf16 v[64:67], v[158:161], v[182:185], v[64:67]
	v_mfma_f32_16x16x32_bf16 v[60:63], v[162:165], v[182:185], v[60:63]
	v_mfma_f32_16x16x32_bf16 v[44:47], v[170:173], v[182:185], v[44:47]
	v_mfma_f32_16x16x32_bf16 v[36:39], v[144:147], v[186:189], v[36:39]
	v_mfma_f32_16x16x32_bf16 v[32:35], v[158:161], v[186:189], v[32:35]
	v_mfma_f32_16x16x32_bf16 v[24:27], v[162:165], v[186:189], v[24:27]
	v_mfma_f32_16x16x32_bf16 v[8:11], v[170:173], v[186:189], v[8:11]
	s_barrier
	v_add_u32_e32 v235, 0x10000, v140
	v_add_u32_e32 v236, 0x10000, v141
	ds_read_b128 v[174:177], v235
	ds_read_b128 v[144:147], v236 offset:16384
	ds_read_b128 v[158:161], v236 offset:17408
	ds_read_b128 v[162:165], v236 offset:18432
	ds_read_b128 v[170:173], v236 offset:19456
	ds_read_b128 v[178:181], v235 offset:1024
	ds_read_b128 v[182:185], v235 offset:2048
	ds_read_b128 v[186:189], v235 offset:3072
	s_waitcnt lgkmcnt(0)
	s_barrier
	v_mfma_f32_16x16x32_bf16 v[0:3], v[144:147], v[174:177], v[0:3]
	v_mfma_f32_16x16x32_bf16 v[4:7], v[158:161], v[174:177], v[4:7]
	v_mfma_f32_16x16x32_bf16 v[16:19], v[162:165], v[174:177], v[16:19]
	v_mfma_f32_16x16x32_bf16 v[12:15], v[170:173], v[174:177], v[12:15]
	v_mfma_f32_16x16x32_bf16 v[20:23], v[144:147], v[178:181], v[20:23]
	v_mfma_f32_16x16x32_bf16 v[28:31], v[158:161], v[178:181], v[28:31]
	v_mfma_f32_16x16x32_bf16 v[48:51], v[162:165], v[178:181], v[48:51]
	v_mfma_f32_16x16x32_bf16 v[40:43], v[170:173], v[178:181], v[40:43]
	v_mfma_f32_16x16x32_bf16 v[52:55], v[144:147], v[182:185], v[52:55]
	v_mfma_f32_16x16x32_bf16 v[56:59], v[158:161], v[182:185], v[56:59]
	v_mfma_f32_16x16x32_bf16 v[72:75], v[162:165], v[182:185], v[72:75]
	v_mfma_f32_16x16x32_bf16 v[68:71], v[170:173], v[182:185], v[68:71]
	v_mfma_f32_16x16x32_bf16 v[76:79], v[144:147], v[186:189], v[76:79]
	v_mfma_f32_16x16x32_bf16 v[80:83], v[158:161], v[186:189], v[80:83]
	v_mfma_f32_16x16x32_bf16 v[100:103], v[162:165], v[186:189], v[100:103]
	v_mfma_f32_16x16x32_bf16 v[96:99], v[170:173], v[186:189], v[96:99]
	s_barrier
	ds_read_b128 v[174:177], v235 offset:4096
	ds_read_b128 v[178:181], v235 offset:5120
	ds_read_b128 v[182:185], v235 offset:6144
	ds_read_b128 v[186:189], v235 offset:7168
	s_waitcnt vmcnt(0)
	s_waitcnt lgkmcnt(0)
	s_barrier
	v_mfma_f32_16x16x32_bf16 v[104:107], v[144:147], v[174:177], v[104:107]
	v_mfma_f32_16x16x32_bf16 v[108:111], v[158:161], v[174:177], v[108:111]
	v_mfma_f32_16x16x32_bf16 v[120:123], v[162:165], v[174:177], v[120:123]
	v_mfma_f32_16x16x32_bf16 v[116:119], v[170:173], v[174:177], v[116:119]
	v_mfma_f32_16x16x32_bf16 v[124:127], v[144:147], v[178:181], v[124:127]
	v_mfma_f32_16x16x32_bf16 v[112:115], v[158:161], v[178:181], v[112:115]
	v_mfma_f32_16x16x32_bf16 v[92:95], v[162:165], v[178:181], v[92:95]
	v_mfma_f32_16x16x32_bf16 v[88:91], v[170:173], v[178:181], v[88:91]
	v_mfma_f32_16x16x32_bf16 v[84:87], v[144:147], v[182:185], v[84:87]
	v_mfma_f32_16x16x32_bf16 v[64:67], v[158:161], v[182:185], v[64:67]
	v_mfma_f32_16x16x32_bf16 v[60:63], v[162:165], v[182:185], v[60:63]
	v_mfma_f32_16x16x32_bf16 v[44:47], v[170:173], v[182:185], v[44:47]
	v_mfma_f32_16x16x32_bf16 v[36:39], v[144:147], v[186:189], v[36:39]
	v_mfma_f32_16x16x32_bf16 v[32:35], v[158:161], v[186:189], v[32:35]
	v_mfma_f32_16x16x32_bf16 v[24:27], v[162:165], v[186:189], v[24:27]
	v_mfma_f32_16x16x32_bf16 v[8:11], v[170:173], v[186:189], v[8:11]
	s_barrier
	v_add_u32_e32 v235, 0x18000, v140
	v_add_u32_e32 v236, 0x18000, v141
	ds_read_b128 v[174:177], v235
	ds_read_b128 v[144:147], v236 offset:16384
	ds_read_b128 v[158:161], v236 offset:17408
	ds_read_b128 v[162:165], v236 offset:18432
	ds_read_b128 v[170:173], v236 offset:19456
	ds_read_b128 v[178:181], v235 offset:1024
	ds_read_b128 v[182:185], v235 offset:2048
	ds_read_b128 v[186:189], v235 offset:3072
	s_waitcnt lgkmcnt(0)
	s_barrier
	v_mfma_f32_16x16x32_bf16 v[0:3], v[144:147], v[174:177], v[0:3]
	v_mfma_f32_16x16x32_bf16 v[4:7], v[158:161], v[174:177], v[4:7]
	v_mfma_f32_16x16x32_bf16 v[16:19], v[162:165], v[174:177], v[16:19]
	v_mfma_f32_16x16x32_bf16 v[12:15], v[170:173], v[174:177], v[12:15]
	v_mfma_f32_16x16x32_bf16 v[20:23], v[144:147], v[178:181], v[20:23]
	v_mfma_f32_16x16x32_bf16 v[28:31], v[158:161], v[178:181], v[28:31]
	v_mfma_f32_16x16x32_bf16 v[48:51], v[162:165], v[178:181], v[48:51]
	v_mfma_f32_16x16x32_bf16 v[40:43], v[170:173], v[178:181], v[40:43]
	v_mfma_f32_16x16x32_bf16 v[52:55], v[144:147], v[182:185], v[52:55]
	v_mfma_f32_16x16x32_bf16 v[56:59], v[158:161], v[182:185], v[56:59]
	v_mfma_f32_16x16x32_bf16 v[72:75], v[162:165], v[182:185], v[72:75]
	v_mfma_f32_16x16x32_bf16 v[68:71], v[170:173], v[182:185], v[68:71]
	v_mfma_f32_16x16x32_bf16 v[76:79], v[144:147], v[186:189], v[76:79]
	v_mfma_f32_16x16x32_bf16 v[80:83], v[158:161], v[186:189], v[80:83]
	v_mfma_f32_16x16x32_bf16 v[100:103], v[162:165], v[186:189], v[100:103]
	v_mfma_f32_16x16x32_bf16 v[96:99], v[170:173], v[186:189], v[96:99]
	s_barrier
	ds_read_b128 v[174:177], v235 offset:4096
	ds_read_b128 v[178:181], v235 offset:5120
	ds_read_b128 v[182:185], v235 offset:6144
	ds_read_b128 v[186:189], v235 offset:7168
	s_waitcnt lgkmcnt(0)
	s_barrier
	v_mfma_f32_16x16x32_bf16 v[104:107], v[144:147], v[174:177], v[104:107]
	v_mfma_f32_16x16x32_bf16 v[108:111], v[158:161], v[174:177], v[108:111]
	v_mfma_f32_16x16x32_bf16 v[120:123], v[162:165], v[174:177], v[120:123]
	v_mfma_f32_16x16x32_bf16 v[116:119], v[170:173], v[174:177], v[116:119]
	v_mfma_f32_16x16x32_bf16 v[124:127], v[144:147], v[178:181], v[124:127]
	v_mfma_f32_16x16x32_bf16 v[112:115], v[158:161], v[178:181], v[112:115]
	v_mfma_f32_16x16x32_bf16 v[92:95], v[162:165], v[178:181], v[92:95]
	v_mfma_f32_16x16x32_bf16 v[88:91], v[170:173], v[178:181], v[88:91]
	v_mfma_f32_16x16x32_bf16 v[84:87], v[144:147], v[182:185], v[84:87]
	v_mfma_f32_16x16x32_bf16 v[64:67], v[158:161], v[182:185], v[64:67]
	v_mfma_f32_16x16x32_bf16 v[60:63], v[162:165], v[182:185], v[60:63]
	v_mfma_f32_16x16x32_bf16 v[44:47], v[170:173], v[182:185], v[44:47]
	v_mfma_f32_16x16x32_bf16 v[36:39], v[144:147], v[186:189], v[36:39]
	v_mfma_f32_16x16x32_bf16 v[32:35], v[158:161], v[186:189], v[32:35]
	v_mfma_f32_16x16x32_bf16 v[24:27], v[162:165], v[186:189], v[24:27]
	v_mfma_f32_16x16x32_bf16 v[8:11], v[170:173], v[186:189], v[8:11]
	s_barrier
	s_cmp_ge_u32 s98, 0x2000
	s_cbranch_scc1 .Lmg1_done
	s_barrier

; #define GEMM_WAITV(n) asm volatile("s_waitcnt vmcnt(" #n ")" ::: "memory")
; template <bool SWAP>
; __device__ __forceinline__ void gemm_main(f32x4 (&acc)[8][4], const TP& t, int nk, char* lds) {
;     ...
; #pragma unroll 1
;   for (int kt = 0; kt < nk - 3; ++kt) {
;     GEMM_WAITV(8);
;     GEMM_STEP(kt, true)
;   }
; __device__ __forceinline__ void merge_phase(const Params& p, int first, int step, int n, char* lds) {
;     ...
;     gemm_main<true>(acc, cur, 16, lds);
.Lmg2_top:
	s_add_i32 s55, s54, 0xfffe8000
	s_and_b32 s55, s55, 0x18000
	v_add_u32_e32 v235, s55, v141
	v_add_u32_e32 v236, s55, v143
	ds_read_b128 v[214:217], v235
	ds_read_b128 v[198:201], v236 offset:16384
	ds_read_b128 v[202:205], v236 offset:17408
	ds_read_b128 v[206:209], v236 offset:18432
	ds_read_b128 v[210:213], v236 offset:19456
	ds_read_b128 v[218:221], v235 offset:1024
	ds_read_b128 v[222:225], v235 offset:2048
	ds_read_b128 v[226:229], v235 offset:3072
	s_and_b32 s99, s54, 0x18000
	s_add_i32 s99, s99, s98
	s_mov_b32 m0, s99
	v_lshl_add_u64 v[146:147], v[130:131], 0, s[46:47]
	v_lshl_add_u64 v[238:239], v[146:147], 0, s[42:43]
	global_load_lds_dwordx4 v[238:239], off
	s_add_i32 m0, s99, 0x400
	v_lshl_add_u64 v[238:239], v[146:147], 0, s[44:45]
	global_load_lds_dwordx4 v[238:239], off
	s_waitcnt lgkmcnt(0)
	s_barrier
	v_mfma_f32_16x16x32_bf16 v[0:3], v[198:201], v[214:217], v[0:3]
	v_mfma_f32_16x16x32_bf16 v[4:7], v[202:205], v[214:217], v[4:7]
	v_mfma_f32_16x16x32_bf16 v[16:19], v[206:209], v[214:217], v[16:19]
	v_mfma_f32_16x16x32_bf16 v[12:15], v[210:213], v[214:217], v[12:15]
	v_mfma_f32_16x16x32_bf16 v[20:23], v[198:201], v[218:221], v[20:23]
	v_mfma_f32_16x16x32_bf16 v[28:31], v[202:205], v[218:221], v[28:31]
	v_mfma_f32_16x16x32_bf16 v[48:51], v[206:209], v[218:221], v[48:51]
	v_mfma_f32_16x16x32_bf16 v[40:43], v[210:213], v[218:221], v[40:43]
	v_mfma_f32_16x16x32_bf16 v[52:55], v[198:201], v[222:225], v[52:55]
	v_mfma_f32_16x16x32_bf16 v[56:59], v[202:205], v[222:225], v[56:59]
	v_mfma_f32_16x16x32_bf16 v[72:75], v[206:209], v[222:225], v[72:75]
	v_mfma_f32_16x16x32_bf16 v[68:71], v[210:213], v[222:225], v[68:71]
	v_mfma_f32_16x16x32_bf16 v[76:79], v[198:201], v[226:229], v[76:79]
	v_mfma_f32_16x16x32_bf16 v[80:83], v[202:205], v[226:229], v[80:83]
	v_mfma_f32_16x16x32_bf16 v[100:103], v[206:209], v[226:229], v[100:103]
	v_mfma_f32_16x16x32_bf16 v[96:99], v[210:213], v[226:229], v[96:99]
	s_barrier
	ds_read_b128 v[214:217], v235 offset:4096
	ds_read_b128 v[218:221], v235 offset:5120
	ds_read_b128 v[222:225], v235 offset:6144
	ds_read_b128 v[226:229], v235 offset:7168
	s_add_i32 m0, s99, 0x4000
	v_lshl_add_u64 v[238:239], v[132:133], 0, s[46:47]
	global_load_lds_dwordx4 v[238:239], off
	s_add_i32 m0, s99, 0x4400
	v_lshl_add_u64 v[238:239], v[134:135], 0, s[46:47]
	global_load_lds_dwordx4 v[238:239], off
	s_add_u32 s46, s46, 64
	s_addc_u32 s47, s47, 0
	s_add_i32 s54, s54, 0x8000
	s_waitcnt vmcnt(8)
	s_waitcnt lgkmcnt(0)
	s_barrier
	v_mfma_f32_16x16x32_bf16 v[104:107], v[198:201], v[214:217], v[104:107]
	v_mfma_f32_16x16x32_bf16 v[108:111], v[202:205], v[214:217], v[108:111]
	v_mfma_f32_16x16x32_bf16 v[120:123], v[206:209], v[214:217], v[120:123]
	v_mfma_f32_16x16x32_bf16 v[116:119], v[210:213], v[214:217], v[116:119]
	v_mfma_f32_16x16x32_bf16 v[124:127], v[198:201], v[218:221], v[124:127]
	v_mfma_f32_16x16x32_bf16 v[112:115], v[202:205], v[218:221], v[112:115]
	v_mfma_f32_16x16x32_bf16 v[92:95], v[206:209], v[218:221], v[92:95]
	v_mfma_f32_16x16x32_bf16 v[88:91], v[210:213], v[218:221], v[88:91]
	v_mfma_f32_16x16x32_bf16 v[84:87], v[198:201], v[222:225], v[84:87]
	v_mfma_f32_16x16x32_bf16 v[64:67], v[202:205], v[222:225], v[64:67]
	v_mfma_f32_16x16x32_bf16 v[60:63], v[206:209], v[222:225], v[60:63]
	v_mfma_f32_16x16x32_bf16 v[44:47], v[210:213], v[222:225], v[44:47]
	v_mfma_f32_16x16x32_bf16 v[36:39], v[198:201], v[226:229], v[36:39]
	v_mfma_f32_16x16x32_bf16 v[32:35], v[202:205], v[226:229], v[32:35]
	v_mfma_f32_16x16x32_bf16 v[24:27], v[206:209], v[226:229], v[24:27]
	v_mfma_f32_16x16x32_bf16 v[8:11], v[210:213], v[226:229], v[8:11]
	s_barrier
	s_cmpk_lg_i32 s46, 0x340
	s_cbranch_scc1 .Lmg2_top
	v_add_u32_e32 v235, 0x8000, v141
	v_add_u32_e32 v236, 0x8000, v143
	ds_read_b128 v[214:217], v235
	ds_read_b128 v[198:201], v236 offset:16384
	ds_read_b128 v[202:205], v236 offset:17408
	ds_read_b128 v[206:209], v236 offset:18432
	ds_read_b128 v[210:213], v236 offset:19456
	ds_read_b128 v[218:221], v235 offset:1024
	ds_read_b128 v[222:225], v235 offset:2048
	ds_read_b128 v[226:229], v235 offset:3072
	s_waitcnt lgkmcnt(0)
	s_barrier
	v_mfma_f32_16x16x32_bf16 v[0:3], v[198:201], v[214:217], v[0:3]
	v_mfma_f32_16x16x32_bf16 v[4:7], v[202:205], v[214:217], v[4:7]
	v_mfma_f32_16x16x32_bf16 v[16:19], v[206:209], v[214:217], v[16:19]
	v_mfma_f32_16x16x32_bf16 v[12:15], v[210:213], v[214:217], v[12:15]
	v_mfma_f32_16x16x32_bf16 v[20:23], v[198:201], v[218:221], v[20:23]
	v_mfma_f32_16x16x32_bf16 v[28:31], v[202:205], v[218:221], v[28:31]
	v_mfma_f32_16x16x32_bf16 v[48:51], v[206:209], v[218:221], v[48:51]
	v_mfma_f32_16x16x32_bf16 v[40:43], v[210:213], v[218:221], v[40:43]
	v_mfma_f32_16x16x32_bf16 v[52:55], v[198:201], v[222:225], v[52:55]
	v_mfma_f32_16x16x32_bf16 v[56:59], v[202:205], v[222:225], v[56:59]
	v_mfma_f32_16x16x32_bf16 v[72:75], v[206:209], v[222:225], v[72:75]
	v_mfma_f32_16x16x32_bf16 v[68:71], v[210:213], v[222:225], v[68:71]
	v_mfma_f32_16x16x32_bf16 v[76:79], v[198:201], v[226:229], v[76:79]
	v_mfma_f32_16x16x32_bf16 v[80:83], v[202:205], v[226:229], v[80:83]
	v_mfma_f32_16x16x32_bf16 v[100:103], v[206:209], v[226:229], v[100:103]
	v_mfma_f32_16x16x32_bf16 v[96:99], v[210:213], v[226:229], v[96:99]
	s_barrier
	ds_read_b128 v[214:217], v235 offset:4096
	ds_read_b128 v[218:221], v235 offset:5120
	ds_read_b128 v[222:225], v235 offset:6144
	ds_read_b128 v[226:229], v235 offset:7168
	s_waitcnt vmcnt(4)
	s_waitcnt lgkmcnt(0)
	s_barrier
; #define GEMM_WAITV(n) asm volatile("s_waitcnt vmcnt(" #n ")" ::: "memory")
; template <bool SWAP>
; __device__ __forceinline__ void gemm_main(f32x4 (&acc)[8][4], const TP& t, int nk, char* lds) {
;     ...
; #pragma unroll 1
;   for (int kt = nk - 3; kt < nk; ++kt) {
;     const int rem = nk - kt;
;     if (rem == 3) GEMM_WAITV(8); else if (rem == 2) GEMM_WAITV(4); else GEMM_WAITV(0);
;     GEMM_STEP(kt, false)
;   }
;   __builtin_amdgcn_s_barrier();
	v_mfma_f32_16x16x32_bf16 v[104:107], v[198:201], v[214:217], v[104:107]
	v_mfma_f32_16x16x32_bf16 v[108:111], v[202:205], v[214:217], v[108:111]
	v_mfma_f32_16x16x32_bf16 v[120:123], v[206:209], v[214:217], v[120:123]
	v_mfma_f32_16x16x32_bf16 v[116:119], v[210:213], v[214:217], v[116:119]
	v_mfma_f32_16x16x32_bf16 v[124:127], v[198:201], v[218:221], v[124:127]
	v_mfma_f32_16x16x32_bf16 v[112:115], v[202:205], v[218:221], v[112:115]
	v_mfma_f32_16x16x32_bf16 v[92:95], v[206:209], v[218:221], v[92:95]
	v_mfma_f32_16x16x32_bf16 v[88:91], v[210:213], v[218:221], v[88:91]
	v_mfma_f32_16x16x32_bf16 v[84:87], v[198:201], v[222:225], v[84:87]
	v_mfma_f32_16x16x32_bf16 v[64:67], v[202:205], v[222:225], v[64:67]
	v_mfma_f32_16x16x32_bf16 v[60:63], v[206:209], v[222:225], v[60:63]
	v_mfma_f32_16x16x32_bf16 v[44:47], v[210:213], v[222:225], v[44:47]
	v_mfma_f32_16x16x32_bf16 v[36:39], v[198:201], v[226:229], v[36:39]
	v_mfma_f32_16x16x32_bf16 v[32:35], v[202:205], v[226:229], v[32:35]
	v_mfma_f32_16x16x32_bf16 v[24:27], v[206:209], v[226:229], v[24:27]
	v_mfma_f32_16x16x32_bf16 v[8:11], v[210:213], v[226:229], v[8:11]
	s_barrier
	v_add_u32_e32 v235, 0x10000, v141
	v_add_u32_e32 v236, 0x10000, v143
	ds_read_b128 v[214:217], v235
	ds_read_b128 v[198:201], v236 offset:16384
	ds_read_b128 v[202:205], v236 offset:17408
	ds_read_b128 v[206:209], v236 offset:18432
	ds_read_b128 v[210:213], v236 offset:19456
	ds_read_b128 v[218:221], v235 offset:1024
	ds_read_b128 v[222:225], v235 offset:2048
	ds_read_b128 v[226:229], v235 offset:3072
	s_waitcnt lgkmcnt(0)
	s_barrier
	v_mfma_f32_16x16x32_bf16 v[0:3], v[198:201], v[214:217], v[0:3]
	v_mfma_f32_16x16x32_bf16 v[4:7], v[202:205], v[214:217], v[4:7]
	v_mfma_f32_16x16x32_bf16 v[16:19], v[206:209], v[214:217], v[16:19]
	v_mfma_f32_16x16x32_bf16 v[12:15], v[210:213], v[214:217], v[12:15]
	v_mfma_f32_16x16x32_bf16 v[20:23], v[198:201], v[218:221], v[20:23]
	v_mfma_f32_16x16x32_bf16 v[28:31], v[202:205], v[218:221], v[28:31]
	v_mfma_f32_16x16x32_bf16 v[48:51], v[206:209], v[218:221], v[48:51]
	v_mfma_f32_16x16x32_bf16 v[40:43], v[210:213], v[218:221], v[40:43]
	v_mfma_f32_16x16x32_bf16 v[52:55], v[198:201], v[222:225], v[52:55]
	v_mfma_f32_16x16x32_bf16 v[56:59], v[202:205], v[222:225], v[56:59]
	v_mfma_f32_16x16x32_bf16 v[72:75], v[206:209], v[222:225], v[72:75]
	v_mfma_f32_16x16x32_bf16 v[68:71], v[210:213], v[222:225], v[68:71]
	v_mfma_f32_16x16x32_bf16 v[76:79], v[198:201], v[226:229], v[76:79]
	v_mfma_f32_16x16x32_bf16 v[80:83], v[202:205], v[226:229], v[80:83]
	v_mfma_f32_16x16x32_bf16 v[100:103], v[206:209], v[226:229], v[100:103]
	v_mfma_f32_16x16x32_bf16 v[96:99], v[210:213], v[226:229], v[96:99]
	s_barrier
	ds_read_b128 v[214:217], v235 offset:4096
	ds_read_b128 v[218:221], v235 offset:5120
	ds_read_b128 v[222:225], v235 offset:6144
	ds_read_b128 v[226:229], v235 offset:7168
	s_waitcnt vmcnt(0)
	s_waitcnt lgkmcnt(0)
	s_barrier
	v_mfma_f32_16x16x32_bf16 v[104:107], v[198:201], v[214:217], v[104:107]
	v_mfma_f32_16x16x32_bf16 v[108:111], v[202:205], v[214:217], v[108:111]
	v_mfma_f32_16x16x32_bf16 v[120:123], v[206:209], v[214:217], v[120:123]
	v_mfma_f32_16x16x32_bf16 v[116:119], v[210:213], v[214:217], v[116:119]
	v_mfma_f32_16x16x32_bf16 v[124:127], v[198:201], v[218:221], v[124:127]
	v_mfma_f32_16x16x32_bf16 v[112:115], v[202:205], v[218:221], v[112:115]
	v_mfma_f32_16x16x32_bf16 v[92:95], v[206:209], v[218:221], v[92:95]
	v_mfma_f32_16x16x32_bf16 v[88:91], v[210:213], v[218:221], v[88:91]
	v_mfma_f32_16x16x32_bf16 v[84:87], v[198:201], v[222:225], v[84:87]
	v_mfma_f32_16x16x32_bf16 v[64:67], v[202:205], v[222:225], v[64:67]
	v_mfma_f32_16x16x32_bf16 v[60:63], v[206:209], v[222:225], v[60:63]
	v_mfma_f32_16x16x32_bf16 v[44:47], v[210:213], v[222:225], v[44:47]
	v_mfma_f32_16x16x32_bf16 v[36:39], v[198:201], v[226:229], v[36:39]
	v_mfma_f32_16x16x32_bf16 v[32:35], v[202:205], v[226:229], v[32:35]
	v_mfma_f32_16x16x32_bf16 v[24:27], v[206:209], v[226:229], v[24:27]
	v_mfma_f32_16x16x32_bf16 v[8:11], v[210:213], v[226:229], v[8:11]
	s_barrier
	v_add_u32_e32 v235, 0x18000, v141
	v_add_u32_e32 v236, 0x18000, v143
	ds_read_b128 v[214:217], v235
	ds_read_b128 v[198:201], v236 offset:16384
	ds_read_b128 v[202:205], v236 offset:17408
	ds_read_b128 v[206:209], v236 offset:18432
	ds_read_b128 v[210:213], v236 offset:19456
	ds_read_b128 v[218:221], v235 offset:1024
	ds_read_b128 v[222:225], v235 offset:2048
	ds_read_b128 v[226:229], v235 offset:3072
	s_waitcnt lgkmcnt(0)
	s_barrier
	v_mfma_f32_16x16x32_bf16 v[0:3], v[198:201], v[214:217], v[0:3]
	v_mfma_f32_16x16x32_bf16 v[4:7], v[202:205], v[214:217], v[4:7]
	v_mfma_f32_16x16x32_bf16 v[16:19], v[206:209], v[214:217], v[16:19]
	v_mfma_f32_16x16x32_bf16 v[12:15], v[210:213], v[214:217], v[12:15]
	v_mfma_f32_16x16x32_bf16 v[20:23], v[198:201], v[218:221], v[20:23]
	v_mfma_f32_16x16x32_bf16 v[28:31], v[202:205], v[218:221], v[28:31]
	v_mfma_f32_16x16x32_bf16 v[48:51], v[206:209], v[218:221], v[48:51]
	v_mfma_f32_16x16x32_bf16 v[40:43], v[210:213], v[218:221], v[40:43]
	v_mfma_f32_16x16x32_bf16 v[52:55], v[198:201], v[222:225], v[52:55]
	v_mfma_f32_16x16x32_bf16 v[56:59], v[202:205], v[222:225], v[56:59]
	v_mfma_f32_16x16x32_bf16 v[72:75], v[206:209], v[222:225], v[72:75]
	v_mfma_f32_16x16x32_bf16 v[68:71], v[210:213], v[222:225], v[68:71]
	v_mfma_f32_16x16x32_bf16 v[76:79], v[198:201], v[226:229], v[76:79]
	v_mfma_f32_16x16x32_bf16 v[80:83], v[202:205], v[226:229], v[80:83]
	v_mfma_f32_16x16x32_bf16 v[100:103], v[206:209], v[226:229], v[100:103]
	v_mfma_f32_16x16x32_bf16 v[96:99], v[210:213], v[226:229], v[96:99]
	s_barrier
	ds_read_b128 v[214:217], v235 offset:4096
	ds_read_b128 v[218:221], v235 offset:5120
	ds_read_b128 v[222:225], v235 offset:6144
	ds_read_b128 v[226:229], v235 offset:7168
	s_waitcnt lgkmcnt(0)
	s_barrier
	v_mfma_f32_16x16x32_bf16 v[104:107], v[198:201], v[214:217], v[104:107]
	v_mfma_f32_16x16x32_bf16 v[108:111], v[202:205], v[214:217], v[108:111]
	v_mfma_f32_16x16x32_bf16 v[120:123], v[206:209], v[214:217], v[120:123]
	v_mfma_f32_16x16x32_bf16 v[116:119], v[210:213], v[214:217], v[116:119]
	v_mfma_f32_16x16x32_bf16 v[124:127], v[198:201], v[218:221], v[124:127]
	v_mfma_f32_16x16x32_bf16 v[112:115], v[202:205], v[218:221], v[112:115]
	v_mfma_f32_16x16x32_bf16 v[92:95], v[206:209], v[218:221], v[92:95]
	v_mfma_f32_16x16x32_bf16 v[88:91], v[210:213], v[218:221], v[88:91]
	v_mfma_f32_16x16x32_bf16 v[84:87], v[198:201], v[222:225], v[84:87]
	v_mfma_f32_16x16x32_bf16 v[64:67], v[202:205], v[222:225], v[64:67]
	v_mfma_f32_16x16x32_bf16 v[60:63], v[206:209], v[222:225], v[60:63]
	v_mfma_f32_16x16x32_bf16 v[44:47], v[210:213], v[222:225], v[44:47]
	v_mfma_f32_16x16x32_bf16 v[36:39], v[198:201], v[226:229], v[36:39]
	v_mfma_f32_16x16x32_bf16 v[32:35], v[202:205], v[226:229], v[32:35]
	v_mfma_f32_16x16x32_bf16 v[24:27], v[206:209], v[226:229], v[24:27]
	v_mfma_f32_16x16x32_bf16 v[8:11], v[210:213], v[226:229], v[8:11]
	s_barrier
	s_cmp_ge_u32 s98, 0x2000
	s_cbranch_scc1 .Lmg2_done
	s_barrier

; #define GEMM_WAITV(n) asm volatile("s_waitcnt vmcnt(" #n ")" ::: "memory")
; template <bool SWAP>
; __device__ __forceinline__ void gemm_main(f32x4 (&acc)[8][4], const TP& t, int nk, char* lds) {
;     ...
; #pragma unroll 1
;   for (int kt = 0; kt < nk - 3; ++kt) {
;     GEMM_WAITV(8);
;     GEMM_STEP(kt, true)
;   }
.Lg3_top:
	s_add_i32 s37, s36, 0xfffe8000
	s_and_b32 s37, s37, 0x18000
	v_add_u32_e32 v235, s37, v144
	v_add_u32_e32 v236, s37, v149
	ds_read_b128 v[174:177], v235
	ds_read_b128 v[156:159], v236 offset:16384
	ds_read_b128 v[160:163], v236 offset:17408
	ds_read_b128 v[164:167], v236 offset:18432
	ds_read_b128 v[170:173], v236 offset:19456
	ds_read_b128 v[178:181], v235 offset:1024
	ds_read_b128 v[182:185], v235 offset:2048
	ds_read_b128 v[186:189], v235 offset:3072
	s_and_b32 s99, s36, 0x18000
	s_add_i32 s99, s99, s98
	s_mov_b32 m0, s99
	v_lshl_add_u64 v[238:239], v[128:129], 0, s[30:31]
	global_load_lds_dwordx4 v[238:239], off
	s_add_i32 m0, s99, 0x400
	s_nop 0
	global_load_lds_dwordx4 v[128:129], off
	s_waitcnt lgkmcnt(0)
	s_barrier
	v_mfma_f32_16x16x32_bf16 v[124:127], v[156:159], v[174:177], v[124:127]
	v_mfma_f32_16x16x32_bf16 v[120:123], v[160:163], v[174:177], v[120:123]
	v_mfma_f32_16x16x32_bf16 v[116:119], v[164:167], v[174:177], v[116:119]
	v_mfma_f32_16x16x32_bf16 v[112:115], v[170:173], v[174:177], v[112:115]
	v_mfma_f32_16x16x32_bf16 v[108:111], v[156:159], v[178:181], v[108:111]
	v_mfma_f32_16x16x32_bf16 v[104:107], v[160:163], v[178:181], v[104:107]
	v_mfma_f32_16x16x32_bf16 v[100:103], v[164:167], v[178:181], v[100:103]
	v_mfma_f32_16x16x32_bf16 v[96:99], v[170:173], v[178:181], v[96:99]
	v_mfma_f32_16x16x32_bf16 v[92:95], v[156:159], v[182:185], v[92:95]
	v_mfma_f32_16x16x32_bf16 v[88:91], v[160:163], v[182:185], v[88:91]
	v_mfma_f32_16x16x32_bf16 v[84:87], v[164:167], v[182:185], v[84:87]
	v_mfma_f32_16x16x32_bf16 v[80:83], v[170:173], v[182:185], v[80:83]
	v_mfma_f32_16x16x32_bf16 v[76:79], v[156:159], v[186:189], v[76:79]
	v_mfma_f32_16x16x32_bf16 v[72:75], v[160:163], v[186:189], v[72:75]
	v_mfma_f32_16x16x32_bf16 v[68:71], v[164:167], v[186:189], v[68:71]
	v_mfma_f32_16x16x32_bf16 v[64:67], v[170:173], v[186:189], v[64:67]
	s_barrier
	ds_read_b128 v[174:177], v235 offset:4096
	ds_read_b128 v[178:181], v235 offset:5120
	ds_read_b128 v[182:185], v235 offset:6144
	ds_read_b128 v[186:189], v235 offset:7168
	s_add_i32 m0, s99, 0x4000
	s_nop 0
	global_load_lds_dwordx4 v[130:131], off
	s_add_i32 m0, s99, 0x4400
	s_nop 0
	global_load_lds_dwordx4 v[132:133], off
	v_lshl_add_u64 v[128:129], v[128:129], 0, 64
	v_lshl_add_u64 v[130:131], v[130:131], 0, 64
	v_lshl_add_u64 v[132:133], v[132:133], 0, 64
	s_add_i32 s36, s36, 0x8000
	s_waitcnt vmcnt(8)
	s_waitcnt lgkmcnt(0)
	s_barrier
	v_mfma_f32_16x16x32_bf16 v[60:63], v[156:159], v[174:177], v[60:63]
	v_mfma_f32_16x16x32_bf16 v[56:59], v[160:163], v[174:177], v[56:59]
	v_mfma_f32_16x16x32_bf16 v[52:55], v[164:167], v[174:177], v[52:55]
	v_mfma_f32_16x16x32_bf16 v[48:51], v[170:173], v[174:177], v[48:51]
	v_mfma_f32_16x16x32_bf16 v[44:47], v[156:159], v[178:181], v[44:47]
	v_mfma_f32_16x16x32_bf16 v[40:43], v[160:163], v[178:181], v[40:43]
	v_mfma_f32_16x16x32_bf16 v[36:39], v[164:167], v[178:181], v[36:39]
	v_mfma_f32_16x16x32_bf16 v[32:35], v[170:173], v[178:181], v[32:35]
	v_mfma_f32_16x16x32_bf16 v[28:31], v[156:159], v[182:185], v[28:31]
	v_mfma_f32_16x16x32_bf16 v[24:27], v[160:163], v[182:185], v[24:27]
	v_mfma_f32_16x16x32_bf16 v[20:23], v[164:167], v[182:185], v[20:23]
	v_mfma_f32_16x16x32_bf16 v[16:19], v[170:173], v[182:185], v[16:19]
	v_mfma_f32_16x16x32_bf16 v[12:15], v[156:159], v[186:189], v[12:15]
	v_mfma_f32_16x16x32_bf16 v[8:11], v[160:163], v[186:189], v[8:11]
	v_mfma_f32_16x16x32_bf16 v[4:7], v[164:167], v[186:189], v[4:7]
	v_mfma_f32_16x16x32_bf16 v[0:3], v[170:173], v[186:189], v[0:3]
	s_barrier
	s_cmp_lg_u32 s36, 0x100000
	s_cbranch_scc1 .Lg3_top
	v_add_u32_e32 v235, 0x8000, v144
	v_add_u32_e32 v236, 0x8000, v149
	ds_read_b128 v[174:177], v235
	ds_read_b128 v[156:159], v236 offset:16384
	ds_read_b128 v[160:163], v236 offset:17408
	ds_read_b128 v[164:167], v236 offset:18432
	ds_read_b128 v[170:173], v236 offset:19456
	ds_read_b128 v[178:181], v235 offset:1024
	ds_read_b128 v[182:185], v235 offset:2048
	ds_read_b128 v[186:189], v235 offset:3072
	s_waitcnt lgkmcnt(0)
	s_barrier
	v_mfma_f32_16x16x32_bf16 v[124:127], v[156:159], v[174:177], v[124:127]
	v_mfma_f32_16x16x32_bf16 v[120:123], v[160:163], v[174:177], v[120:123]
	v_mfma_f32_16x16x32_bf16 v[116:119], v[164:167], v[174:177], v[116:119]
	v_mfma_f32_16x16x32_bf16 v[112:115], v[170:173], v[174:177], v[112:115]
	v_mfma_f32_16x16x32_bf16 v[108:111], v[156:159], v[178:181], v[108:111]
	v_mfma_f32_16x16x32_bf16 v[104:107], v[160:163], v[178:181], v[104:107]
	v_mfma_f32_16x16x32_bf16 v[100:103], v[164:167], v[178:181], v[100:103]
	v_mfma_f32_16x16x32_bf16 v[96:99], v[170:173], v[178:181], v[96:99]
	v_mfma_f32_16x16x32_bf16 v[92:95], v[156:159], v[182:185], v[92:95]
	v_mfma_f32_16x16x32_bf16 v[88:91], v[160:163], v[182:185], v[88:91]
	v_mfma_f32_16x16x32_bf16 v[84:87], v[164:167], v[182:185], v[84:87]
	v_mfma_f32_16x16x32_bf16 v[80:83], v[170:173], v[182:185], v[80:83]
	v_mfma_f32_16x16x32_bf16 v[76:79], v[156:159], v[186:189], v[76:79]
	v_mfma_f32_16x16x32_bf16 v[72:75], v[160:163], v[186:189], v[72:75]
	v_mfma_f32_16x16x32_bf16 v[68:71], v[164:167], v[186:189], v[68:71]
	v_mfma_f32_16x16x32_bf16 v[64:67], v[170:173], v[186:189], v[64:67]
	s_barrier
	ds_read_b128 v[174:177], v235 offset:4096
	ds_read_b128 v[178:181], v235 offset:5120
	ds_read_b128 v[182:185], v235 offset:6144
	ds_read_b128 v[186:189], v235 offset:7168
	s_waitcnt vmcnt(4)
	s_waitcnt lgkmcnt(0)
	s_barrier
; #define GEMM_WAITV(n) asm volatile("s_waitcnt vmcnt(" #n ")" ::: "memory")
; template <bool SWAP>
; __device__ __forceinline__ void gemm_main(f32x4 (&acc)[8][4], const TP& t, int nk, char* lds) {
;     ...
; #pragma unroll 1
;   for (int kt = nk - 3; kt < nk; ++kt) {
;     const int rem = nk - kt;
;     if (rem == 3) GEMM_WAITV(8); else if (rem == 2) GEMM_WAITV(4); else GEMM_WAITV(0);
;     GEMM_STEP(kt, false)
;   }
;   __builtin_amdgcn_s_barrier();
	v_mfma_f32_16x16x32_bf16 v[60:63], v[156:159], v[174:177], v[60:63]
	v_mfma_f32_16x16x32_bf16 v[56:59], v[160:163], v[174:177], v[56:59]
	v_mfma_f32_16x16x32_bf16 v[52:55], v[164:167], v[174:177], v[52:55]
	v_mfma_f32_16x16x32_bf16 v[48:51], v[170:173], v[174:177], v[48:51]
	v_mfma_f32_16x16x32_bf16 v[44:47], v[156:159], v[178:181], v[44:47]
	v_mfma_f32_16x16x32_bf16 v[40:43], v[160:163], v[178:181], v[40:43]
	v_mfma_f32_16x16x32_bf16 v[36:39], v[164:167], v[178:181], v[36:39]
	v_mfma_f32_16x16x32_bf16 v[32:35], v[170:173], v[178:181], v[32:35]
	v_mfma_f32_16x16x32_bf16 v[28:31], v[156:159], v[182:185], v[28:31]
	v_mfma_f32_16x16x32_bf16 v[24:27], v[160:163], v[182:185], v[24:27]
	v_mfma_f32_16x16x32_bf16 v[20:23], v[164:167], v[182:185], v[20:23]
	v_mfma_f32_16x16x32_bf16 v[16:19], v[170:173], v[182:185], v[16:19]
	v_mfma_f32_16x16x32_bf16 v[12:15], v[156:159], v[186:189], v[12:15]
	v_mfma_f32_16x16x32_bf16 v[8:11], v[160:163], v[186:189], v[8:11]
	v_mfma_f32_16x16x32_bf16 v[4:7], v[164:167], v[186:189], v[4:7]
	v_mfma_f32_16x16x32_bf16 v[0:3], v[170:173], v[186:189], v[0:3]
	s_barrier
	v_add_u32_e32 v235, 0x10000, v144
	v_add_u32_e32 v236, 0x10000, v149
	ds_read_b128 v[174:177], v235
	ds_read_b128 v[156:159], v236 offset:16384
	ds_read_b128 v[160:163], v236 offset:17408
	ds_read_b128 v[164:167], v236 offset:18432
	ds_read_b128 v[170:173], v236 offset:19456
	ds_read_b128 v[178:181], v235 offset:1024
	ds_read_b128 v[182:185], v235 offset:2048
	ds_read_b128 v[186:189], v235 offset:3072
	s_waitcnt lgkmcnt(0)
	s_barrier
	v_mfma_f32_16x16x32_bf16 v[124:127], v[156:159], v[174:177], v[124:127]
	v_mfma_f32_16x16x32_bf16 v[120:123], v[160:163], v[174:177], v[120:123]
	v_mfma_f32_16x16x32_bf16 v[116:119], v[164:167], v[174:177], v[116:119]
	v_mfma_f32_16x16x32_bf16 v[112:115], v[170:173], v[174:177], v[112:115]
	v_mfma_f32_16x16x32_bf16 v[108:111], v[156:159], v[178:181], v[108:111]
	v_mfma_f32_16x16x32_bf16 v[104:107], v[160:163], v[178:181], v[104:107]
	v_mfma_f32_16x16x32_bf16 v[100:103], v[164:167], v[178:181], v[100:103]
	v_mfma_f32_16x16x32_bf16 v[96:99], v[170:173], v[178:181], v[96:99]
	v_mfma_f32_16x16x32_bf16 v[92:95], v[156:159], v[182:185], v[92:95]
	v_mfma_f32_16x16x32_bf16 v[88:91], v[160:163], v[182:185], v[88:91]
	v_mfma_f32_16x16x32_bf16 v[84:87], v[164:167], v[182:185], v[84:87]
	v_mfma_f32_16x16x32_bf16 v[80:83], v[170:173], v[182:185], v[80:83]
	v_mfma_f32_16x16x32_bf16 v[76:79], v[156:159], v[186:189], v[76:79]
	v_mfma_f32_16x16x32_bf16 v[72:75], v[160:163], v[186:189], v[72:75]
	v_mfma_f32_16x16x32_bf16 v[68:71], v[164:167], v[186:189], v[68:71]
	v_mfma_f32_16x16x32_bf16 v[64:67], v[170:173], v[186:189], v[64:67]
	s_barrier
	ds_read_b128 v[174:177], v235 offset:4096
	ds_read_b128 v[178:181], v235 offset:5120
	ds_read_b128 v[182:185], v235 offset:6144
	ds_read_b128 v[186:189], v235 offset:7168
	s_waitcnt vmcnt(0)
	s_waitcnt lgkmcnt(0)
	s_barrier
	v_mfma_f32_16x16x32_bf16 v[60:63], v[156:159], v[174:177], v[60:63]
	v_mfma_f32_16x16x32_bf16 v[56:59], v[160:163], v[174:177], v[56:59]
	v_mfma_f32_16x16x32_bf16 v[52:55], v[164:167], v[174:177], v[52:55]
	v_mfma_f32_16x16x32_bf16 v[48:51], v[170:173], v[174:177], v[48:51]
	v_mfma_f32_16x16x32_bf16 v[44:47], v[156:159], v[178:181], v[44:47]
	v_mfma_f32_16x16x32_bf16 v[40:43], v[160:163], v[178:181], v[40:43]
	v_mfma_f32_16x16x32_bf16 v[36:39], v[164:167], v[178:181], v[36:39]
	v_mfma_f32_16x16x32_bf16 v[32:35], v[170:173], v[178:181], v[32:35]
	v_mfma_f32_16x16x32_bf16 v[28:31], v[156:159], v[182:185], v[28:31]
	v_mfma_f32_16x16x32_bf16 v[24:27], v[160:163], v[182:185], v[24:27]
	v_mfma_f32_16x16x32_bf16 v[20:23], v[164:167], v[182:185], v[20:23]
	v_mfma_f32_16x16x32_bf16 v[16:19], v[170:173], v[182:185], v[16:19]
	v_mfma_f32_16x16x32_bf16 v[12:15], v[156:159], v[186:189], v[12:15]
	v_mfma_f32_16x16x32_bf16 v[8:11], v[160:163], v[186:189], v[8:11]
	v_mfma_f32_16x16x32_bf16 v[4:7], v[164:167], v[186:189], v[4:7]
	v_mfma_f32_16x16x32_bf16 v[0:3], v[170:173], v[186:189], v[0:3]
	s_barrier
	v_add_u32_e32 v235, 0x18000, v144
	v_add_u32_e32 v236, 0x18000, v149
	ds_read_b128 v[174:177], v235
	ds_read_b128 v[156:159], v236 offset:16384
	ds_read_b128 v[160:163], v236 offset:17408
	ds_read_b128 v[164:167], v236 offset:18432
	ds_read_b128 v[170:173], v236 offset:19456
	ds_read_b128 v[178:181], v235 offset:1024
	ds_read_b128 v[182:185], v235 offset:2048
	ds_read_b128 v[186:189], v235 offset:3072
	s_waitcnt lgkmcnt(0)
	s_barrier
	v_mfma_f32_16x16x32_bf16 v[124:127], v[156:159], v[174:177], v[124:127]
	v_mfma_f32_16x16x32_bf16 v[120:123], v[160:163], v[174:177], v[120:123]
	v_mfma_f32_16x16x32_bf16 v[116:119], v[164:167], v[174:177], v[116:119]
	v_mfma_f32_16x16x32_bf16 v[112:115], v[170:173], v[174:177], v[112:115]
	v_mfma_f32_16x16x32_bf16 v[108:111], v[156:159], v[178:181], v[108:111]
	v_mfma_f32_16x16x32_bf16 v[104:107], v[160:163], v[178:181], v[104:107]
	v_mfma_f32_16x16x32_bf16 v[100:103], v[164:167], v[178:181], v[100:103]
	v_mfma_f32_16x16x32_bf16 v[96:99], v[170:173], v[178:181], v[96:99]
	v_mfma_f32_16x16x32_bf16 v[92:95], v[156:159], v[182:185], v[92:95]
	v_mfma_f32_16x16x32_bf16 v[88:91], v[160:163], v[182:185], v[88:91]
	v_mfma_f32_16x16x32_bf16 v[84:87], v[164:167], v[182:185], v[84:87]
	v_mfma_f32_16x16x32_bf16 v[80:83], v[170:173], v[182:185], v[80:83]
	v_mfma_f32_16x16x32_bf16 v[76:79], v[156:159], v[186:189], v[76:79]
	v_mfma_f32_16x16x32_bf16 v[72:75], v[160:163], v[186:189], v[72:75]
	v_mfma_f32_16x16x32_bf16 v[68:71], v[164:167], v[186:189], v[68:71]
	v_mfma_f32_16x16x32_bf16 v[64:67], v[170:173], v[186:189], v[64:67]
	s_barrier
	ds_read_b128 v[174:177], v235 offset:4096
	ds_read_b128 v[178:181], v235 offset:5120
	ds_read_b128 v[182:185], v235 offset:6144
	ds_read_b128 v[186:189], v235 offset:7168
	s_waitcnt lgkmcnt(0)
	s_barrier
	v_mfma_f32_16x16x32_bf16 v[60:63], v[156:159], v[174:177], v[60:63]
	v_mfma_f32_16x16x32_bf16 v[56:59], v[160:163], v[174:177], v[56:59]
	v_mfma_f32_16x16x32_bf16 v[52:55], v[164:167], v[174:177], v[52:55]
	v_mfma_f32_16x16x32_bf16 v[48:51], v[170:173], v[174:177], v[48:51]
	v_mfma_f32_16x16x32_bf16 v[44:47], v[156:159], v[178:181], v[44:47]
	v_mfma_f32_16x16x32_bf16 v[40:43], v[160:163], v[178:181], v[40:43]
	v_mfma_f32_16x16x32_bf16 v[36:39], v[164:167], v[178:181], v[36:39]
	v_mfma_f32_16x16x32_bf16 v[32:35], v[170:173], v[178:181], v[32:35]
	v_mfma_f32_16x16x32_bf16 v[28:31], v[156:159], v[182:185], v[28:31]
	v_mfma_f32_16x16x32_bf16 v[24:27], v[160:163], v[182:185], v[24:27]
	v_mfma_f32_16x16x32_bf16 v[20:23], v[164:167], v[182:185], v[20:23]
	v_mfma_f32_16x16x32_bf16 v[16:19], v[170:173], v[182:185], v[16:19]
	v_mfma_f32_16x16x32_bf16 v[12:15], v[156:159], v[186:189], v[12:15]
	v_mfma_f32_16x16x32_bf16 v[8:11], v[160:163], v[186:189], v[8:11]
	v_mfma_f32_16x16x32_bf16 v[4:7], v[164:167], v[186:189], v[4:7]
	v_mfma_f32_16x16x32_bf16 v[0:3], v[170:173], v[186:189], v[0:3]
	s_barrier
	s_cmp_ge_u32 s98, 0x2000
	s_cbranch_scc1 .Lg3_done
	s_barrier

; #define GEMM_WAITV(n) asm volatile("s_waitcnt vmcnt(" #n ")" ::: "memory")
; template <bool SWAP>
; __device__ __forceinline__ void gemm_main(f32x4 (&acc)[8][4], const TP& t, int nk, char* lds) {
;     ...
; #pragma unroll 1
;   for (int kt = 0; kt < nk - 3; ++kt) {
;     GEMM_WAITV(8);
;     GEMM_STEP(kt, true)
;   }
.Lmoe1_top:
	s_add_i32 s21, s20, 0xfffe8000
	s_and_b32 s21, s21, 0x18000
	v_add_u32_e32 v235, s21, v160
	v_add_u32_e32 v236, s21, v161
	ds_read_b128 v[182:185], v235
	ds_read_b128 v[164:167], v236 offset:16384
	ds_read_b128 v[170:173], v236 offset:17408
	ds_read_b128 v[174:177], v236 offset:18432
	ds_read_b128 v[178:181], v236 offset:19456
	ds_read_b128 v[186:189], v235 offset:1024
	ds_read_b128 v[190:193], v235 offset:2048
	ds_read_b128 v[194:197], v235 offset:3072
	s_and_b32 s99, s20, 0x18000
	s_add_i32 s99, s99, s98
	s_mov_b32 m0, s99
	s_nop 0
	global_load_lds_dwordx4 v[136:137], off
	s_add_i32 m0, s99, 0x400
	s_nop 0
	global_load_lds_dwordx4 v[138:139], off
	s_waitcnt lgkmcnt(0)
	s_barrier
	v_mfma_f32_16x16x32_bf16 v[124:127], v[164:167], v[182:185], v[124:127]
	v_mfma_f32_16x16x32_bf16 v[120:123], v[170:173], v[182:185], v[120:123]
	v_mfma_f32_16x16x32_bf16 v[116:119], v[174:177], v[182:185], v[116:119]
	v_mfma_f32_16x16x32_bf16 v[112:115], v[178:181], v[182:185], v[112:115]
	v_mfma_f32_16x16x32_bf16 v[108:111], v[164:167], v[186:189], v[108:111]
	v_mfma_f32_16x16x32_bf16 v[104:107], v[170:173], v[186:189], v[104:107]
	v_mfma_f32_16x16x32_bf16 v[100:103], v[174:177], v[186:189], v[100:103]
	v_mfma_f32_16x16x32_bf16 v[96:99], v[178:181], v[186:189], v[96:99]
	v_mfma_f32_16x16x32_bf16 v[92:95], v[164:167], v[190:193], v[92:95]
	v_mfma_f32_16x16x32_bf16 v[88:91], v[170:173], v[190:193], v[88:91]
	v_mfma_f32_16x16x32_bf16 v[84:87], v[174:177], v[190:193], v[84:87]
	v_mfma_f32_16x16x32_bf16 v[80:83], v[178:181], v[190:193], v[80:83]
	v_mfma_f32_16x16x32_bf16 v[76:79], v[164:167], v[194:197], v[76:79]
	v_mfma_f32_16x16x32_bf16 v[72:75], v[170:173], v[194:197], v[72:75]
	v_mfma_f32_16x16x32_bf16 v[68:71], v[174:177], v[194:197], v[68:71]
	v_mfma_f32_16x16x32_bf16 v[64:67], v[178:181], v[194:197], v[64:67]
	s_barrier
	ds_read_b128 v[182:185], v235 offset:4096
	ds_read_b128 v[186:189], v235 offset:5120
	ds_read_b128 v[190:193], v235 offset:6144
	ds_read_b128 v[194:197], v235 offset:7168
	s_add_i32 m0, s99, 0x4000
	s_nop 0
	global_load_lds_dwordx4 v[140:141], off
	s_add_i32 m0, s99, 0x4400
	s_nop 0
	global_load_lds_dwordx4 v[142:143], off
	v_lshl_add_u64 v[136:137], v[136:137], 0, 64
	v_lshl_add_u64 v[138:139], v[138:139], 0, 64
	v_lshl_add_u64 v[140:141], v[140:141], 0, 64
	v_lshl_add_u64 v[142:143], v[142:143], 0, 64
	s_add_i32 s20, s20, 0x8000
	s_waitcnt vmcnt(8)
	s_waitcnt lgkmcnt(0)
	s_barrier
	v_mfma_f32_16x16x32_bf16 v[60:63], v[164:167], v[182:185], v[60:63]
	v_mfma_f32_16x16x32_bf16 v[56:59], v[170:173], v[182:185], v[56:59]
	v_mfma_f32_16x16x32_bf16 v[52:55], v[174:177], v[182:185], v[52:55]
	v_mfma_f32_16x16x32_bf16 v[48:51], v[178:181], v[182:185], v[48:51]
	v_mfma_f32_16x16x32_bf16 v[44:47], v[164:167], v[186:189], v[44:47]
	v_mfma_f32_16x16x32_bf16 v[40:43], v[170:173], v[186:189], v[40:43]
	v_mfma_f32_16x16x32_bf16 v[36:39], v[174:177], v[186:189], v[36:39]
	v_mfma_f32_16x16x32_bf16 v[32:35], v[178:181], v[186:189], v[32:35]
	v_mfma_f32_16x16x32_bf16 v[28:31], v[164:167], v[190:193], v[28:31]
	v_mfma_f32_16x16x32_bf16 v[24:27], v[170:173], v[190:193], v[24:27]
	v_mfma_f32_16x16x32_bf16 v[20:23], v[174:177], v[190:193], v[20:23]
	v_mfma_f32_16x16x32_bf16 v[16:19], v[178:181], v[190:193], v[16:19]
	v_mfma_f32_16x16x32_bf16 v[12:15], v[164:167], v[194:197], v[12:15]
	v_mfma_f32_16x16x32_bf16 v[8:11], v[170:173], v[194:197], v[8:11]
	v_mfma_f32_16x16x32_bf16 v[4:7], v[174:177], v[194:197], v[4:7]
	v_mfma_f32_16x16x32_bf16 v[0:3], v[178:181], v[194:197], v[0:3]
	s_barrier
	s_cmp_lg_u32 s20, 0x100000
	s_cbranch_scc1 .Lmoe1_top
	v_add_u32_e32 v235, 0x8000, v160
	v_add_u32_e32 v236, 0x8000, v161
	ds_read_b128 v[182:185], v235
	ds_read_b128 v[164:167], v236 offset:16384
	ds_read_b128 v[170:173], v236 offset:17408
	ds_read_b128 v[174:177], v236 offset:18432
	ds_read_b128 v[178:181], v236 offset:19456
	ds_read_b128 v[186:189], v235 offset:1024
	ds_read_b128 v[190:193], v235 offset:2048
	ds_read_b128 v[194:197], v235 offset:3072
	s_waitcnt lgkmcnt(0)
	s_barrier
	v_mfma_f32_16x16x32_bf16 v[124:127], v[164:167], v[182:185], v[124:127]
	v_mfma_f32_16x16x32_bf16 v[120:123], v[170:173], v[182:185], v[120:123]
	v_mfma_f32_16x16x32_bf16 v[116:119], v[174:177], v[182:185], v[116:119]
	v_mfma_f32_16x16x32_bf16 v[112:115], v[178:181], v[182:185], v[112:115]
	v_mfma_f32_16x16x32_bf16 v[108:111], v[164:167], v[186:189], v[108:111]
	v_mfma_f32_16x16x32_bf16 v[104:107], v[170:173], v[186:189], v[104:107]
	v_mfma_f32_16x16x32_bf16 v[100:103], v[174:177], v[186:189], v[100:103]
	v_mfma_f32_16x16x32_bf16 v[96:99], v[178:181], v[186:189], v[96:99]
	v_mfma_f32_16x16x32_bf16 v[92:95], v[164:167], v[190:193], v[92:95]
	v_mfma_f32_16x16x32_bf16 v[88:91], v[170:173], v[190:193], v[88:91]
	v_mfma_f32_16x16x32_bf16 v[84:87], v[174:177], v[190:193], v[84:87]
	v_mfma_f32_16x16x32_bf16 v[80:83], v[178:181], v[190:193], v[80:83]
	v_mfma_f32_16x16x32_bf16 v[76:79], v[164:167], v[194:197], v[76:79]
	v_mfma_f32_16x16x32_bf16 v[72:75], v[170:173], v[194:197], v[72:75]
	v_mfma_f32_16x16x32_bf16 v[68:71], v[174:177], v[194:197], v[68:71]
	v_mfma_f32_16x16x32_bf16 v[64:67], v[178:181], v[194:197], v[64:67]
	s_barrier
	ds_read_b128 v[182:185], v235 offset:4096
	ds_read_b128 v[186:189], v235 offset:5120
	ds_read_b128 v[190:193], v235 offset:6144
	ds_read_b128 v[194:197], v235 offset:7168
	s_waitcnt vmcnt(4)
	s_waitcnt lgkmcnt(0)
	s_barrier
; #define GEMM_WAITV(n) asm volatile("s_waitcnt vmcnt(" #n ")" ::: "memory")
; template <bool SWAP>
; __device__ __forceinline__ void gemm_main(f32x4 (&acc)[8][4], const TP& t, int nk, char* lds) {
;     ...
; #pragma unroll 1
;   for (int kt = nk - 3; kt < nk; ++kt) {
;     const int rem = nk - kt;
;     if (rem == 3) GEMM_WAITV(8); else if (rem == 2) GEMM_WAITV(4); else GEMM_WAITV(0);
;     GEMM_STEP(kt, false)
;   }
;   __builtin_amdgcn_s_barrier();
	v_mfma_f32_16x16x32_bf16 v[60:63], v[164:167], v[182:185], v[60:63]
	v_mfma_f32_16x16x32_bf16 v[56:59], v[170:173], v[182:185], v[56:59]
	v_mfma_f32_16x16x32_bf16 v[52:55], v[174:177], v[182:185], v[52:55]
	v_mfma_f32_16x16x32_bf16 v[48:51], v[178:181], v[182:185], v[48:51]
	v_mfma_f32_16x16x32_bf16 v[44:47], v[164:167], v[186:189], v[44:47]
	v_mfma_f32_16x16x32_bf16 v[40:43], v[170:173], v[186:189], v[40:43]
	v_mfma_f32_16x16x32_bf16 v[36:39], v[174:177], v[186:189], v[36:39]
	v_mfma_f32_16x16x32_bf16 v[32:35], v[178:181], v[186:189], v[32:35]
	v_mfma_f32_16x16x32_bf16 v[28:31], v[164:167], v[190:193], v[28:31]
	v_mfma_f32_16x16x32_bf16 v[24:27], v[170:173], v[190:193], v[24:27]
	v_mfma_f32_16x16x32_bf16 v[20:23], v[174:177], v[190:193], v[20:23]
	v_mfma_f32_16x16x32_bf16 v[16:19], v[178:181], v[190:193], v[16:19]
	v_mfma_f32_16x16x32_bf16 v[12:15], v[164:167], v[194:197], v[12:15]
	v_mfma_f32_16x16x32_bf16 v[8:11], v[170:173], v[194:197], v[8:11]
	v_mfma_f32_16x16x32_bf16 v[4:7], v[174:177], v[194:197], v[4:7]
	v_mfma_f32_16x16x32_bf16 v[0:3], v[178:181], v[194:197], v[0:3]
	s_barrier
	v_add_u32_e32 v235, 0x10000, v160
	v_add_u32_e32 v236, 0x10000, v161
	ds_read_b128 v[182:185], v235
	ds_read_b128 v[164:167], v236 offset:16384
	ds_read_b128 v[170:173], v236 offset:17408
	ds_read_b128 v[174:177], v236 offset:18432
	ds_read_b128 v[178:181], v236 offset:19456
	ds_read_b128 v[186:189], v235 offset:1024
	ds_read_b128 v[190:193], v235 offset:2048
	ds_read_b128 v[194:197], v235 offset:3072
	s_waitcnt lgkmcnt(0)
	s_barrier
	v_mfma_f32_16x16x32_bf16 v[124:127], v[164:167], v[182:185], v[124:127]
	v_mfma_f32_16x16x32_bf16 v[120:123], v[170:173], v[182:185], v[120:123]
	v_mfma_f32_16x16x32_bf16 v[116:119], v[174:177], v[182:185], v[116:119]
	v_mfma_f32_16x16x32_bf16 v[112:115], v[178:181], v[182:185], v[112:115]
	v_mfma_f32_16x16x32_bf16 v[108:111], v[164:167], v[186:189], v[108:111]
	v_mfma_f32_16x16x32_bf16 v[104:107], v[170:173], v[186:189], v[104:107]
	v_mfma_f32_16x16x32_bf16 v[100:103], v[174:177], v[186:189], v[100:103]
	v_mfma_f32_16x16x32_bf16 v[96:99], v[178:181], v[186:189], v[96:99]
	v_mfma_f32_16x16x32_bf16 v[92:95], v[164:167], v[190:193], v[92:95]
	v_mfma_f32_16x16x32_bf16 v[88:91], v[170:173], v[190:193], v[88:91]
	v_mfma_f32_16x16x32_bf16 v[84:87], v[174:177], v[190:193], v[84:87]
	v_mfma_f32_16x16x32_bf16 v[80:83], v[178:181], v[190:193], v[80:83]
	v_mfma_f32_16x16x32_bf16 v[76:79], v[164:167], v[194:197], v[76:79]
	v_mfma_f32_16x16x32_bf16 v[72:75], v[170:173], v[194:197], v[72:75]
	v_mfma_f32_16x16x32_bf16 v[68:71], v[174:177], v[194:197], v[68:71]
	v_mfma_f32_16x16x32_bf16 v[64:67], v[178:181], v[194:197], v[64:67]
	s_barrier
	ds_read_b128 v[182:185], v235 offset:4096
	ds_read_b128 v[186:189], v235 offset:5120
	ds_read_b128 v[190:193], v235 offset:6144
	ds_read_b128 v[194:197], v235 offset:7168
	s_waitcnt vmcnt(0)
	s_waitcnt lgkmcnt(0)
	s_barrier
	v_mfma_f32_16x16x32_bf16 v[60:63], v[164:167], v[182:185], v[60:63]
	v_mfma_f32_16x16x32_bf16 v[56:59], v[170:173], v[182:185], v[56:59]
	v_mfma_f32_16x16x32_bf16 v[52:55], v[174:177], v[182:185], v[52:55]
	v_mfma_f32_16x16x32_bf16 v[48:51], v[178:181], v[182:185], v[48:51]
	v_mfma_f32_16x16x32_bf16 v[44:47], v[164:167], v[186:189], v[44:47]
	v_mfma_f32_16x16x32_bf16 v[40:43], v[170:173], v[186:189], v[40:43]
	v_mfma_f32_16x16x32_bf16 v[36:39], v[174:177], v[186:189], v[36:39]
	v_mfma_f32_16x16x32_bf16 v[32:35], v[178:181], v[186:189], v[32:35]
	v_mfma_f32_16x16x32_bf16 v[28:31], v[164:167], v[190:193], v[28:31]
	v_mfma_f32_16x16x32_bf16 v[24:27], v[170:173], v[190:193], v[24:27]
	v_mfma_f32_16x16x32_bf16 v[20:23], v[174:177], v[190:193], v[20:23]
	v_mfma_f32_16x16x32_bf16 v[16:19], v[178:181], v[190:193], v[16:19]
	v_mfma_f32_16x16x32_bf16 v[12:15], v[164:167], v[194:197], v[12:15]
	v_mfma_f32_16x16x32_bf16 v[8:11], v[170:173], v[194:197], v[8:11]
	v_mfma_f32_16x16x32_bf16 v[4:7], v[174:177], v[194:197], v[4:7]
	v_mfma_f32_16x16x32_bf16 v[0:3], v[178:181], v[194:197], v[0:3]
	s_barrier
	v_add_u32_e32 v235, 0x18000, v160
	v_add_u32_e32 v236, 0x18000, v161
	ds_read_b128 v[182:185], v235
	ds_read_b128 v[164:167], v236 offset:16384
	ds_read_b128 v[170:173], v236 offset:17408
	ds_read_b128 v[174:177], v236 offset:18432
	ds_read_b128 v[178:181], v236 offset:19456
	ds_read_b128 v[186:189], v235 offset:1024
	ds_read_b128 v[190:193], v235 offset:2048
	ds_read_b128 v[194:197], v235 offset:3072
	s_waitcnt lgkmcnt(0)
	s_barrier
	v_mfma_f32_16x16x32_bf16 v[124:127], v[164:167], v[182:185], v[124:127]
	v_mfma_f32_16x16x32_bf16 v[120:123], v[170:173], v[182:185], v[120:123]
	v_mfma_f32_16x16x32_bf16 v[116:119], v[174:177], v[182:185], v[116:119]
	v_mfma_f32_16x16x32_bf16 v[112:115], v[178:181], v[182:185], v[112:115]
	v_mfma_f32_16x16x32_bf16 v[108:111], v[164:167], v[186:189], v[108:111]
	v_mfma_f32_16x16x32_bf16 v[104:107], v[170:173], v[186:189], v[104:107]
	v_mfma_f32_16x16x32_bf16 v[100:103], v[174:177], v[186:189], v[100:103]
	v_mfma_f32_16x16x32_bf16 v[96:99], v[178:181], v[186:189], v[96:99]
	v_mfma_f32_16x16x32_bf16 v[92:95], v[164:167], v[190:193], v[92:95]
	v_mfma_f32_16x16x32_bf16 v[88:91], v[170:173], v[190:193], v[88:91]
	v_mfma_f32_16x16x32_bf16 v[84:87], v[174:177], v[190:193], v[84:87]
	v_mfma_f32_16x16x32_bf16 v[80:83], v[178:181], v[190:193], v[80:83]
	v_mfma_f32_16x16x32_bf16 v[76:79], v[164:167], v[194:197], v[76:79]
	v_mfma_f32_16x16x32_bf16 v[72:75], v[170:173], v[194:197], v[72:75]
	v_mfma_f32_16x16x32_bf16 v[68:71], v[174:177], v[194:197], v[68:71]
	v_mfma_f32_16x16x32_bf16 v[64:67], v[178:181], v[194:197], v[64:67]
	s_barrier
	ds_read_b128 v[182:185], v235 offset:4096
	ds_read_b128 v[186:189], v235 offset:5120
	ds_read_b128 v[190:193], v235 offset:6144
	ds_read_b128 v[194:197], v235 offset:7168
	s_waitcnt lgkmcnt(0)
	s_barrier
	v_mfma_f32_16x16x32_bf16 v[60:63], v[164:167], v[182:185], v[60:63]
	v_mfma_f32_16x16x32_bf16 v[56:59], v[170:173], v[182:185], v[56:59]
	v_mfma_f32_16x16x32_bf16 v[52:55], v[174:177], v[182:185], v[52:55]
	v_mfma_f32_16x16x32_bf16 v[48:51], v[178:181], v[182:185], v[48:51]
	v_mfma_f32_16x16x32_bf16 v[44:47], v[164:167], v[186:189], v[44:47]
	v_mfma_f32_16x16x32_bf16 v[40:43], v[170:173], v[186:189], v[40:43]
	v_mfma_f32_16x16x32_bf16 v[36:39], v[174:177], v[186:189], v[36:39]
	v_mfma_f32_16x16x32_bf16 v[32:35], v[178:181], v[186:189], v[32:35]
	v_mfma_f32_16x16x32_bf16 v[28:31], v[164:167], v[190:193], v[28:31]
	v_mfma_f32_16x16x32_bf16 v[24:27], v[170:173], v[190:193], v[24:27]
	v_mfma_f32_16x16x32_bf16 v[20:23], v[174:177], v[190:193], v[20:23]
	v_mfma_f32_16x16x32_bf16 v[16:19], v[178:181], v[190:193], v[16:19]
	v_mfma_f32_16x16x32_bf16 v[12:15], v[164:167], v[194:197], v[12:15]
	v_mfma_f32_16x16x32_bf16 v[8:11], v[170:173], v[194:197], v[8:11]
	v_mfma_f32_16x16x32_bf16 v[4:7], v[174:177], v[194:197], v[4:7]
	v_mfma_f32_16x16x32_bf16 v[0:3], v[178:181], v[194:197], v[0:3]
	s_barrier
	s_cmp_ge_u32 s98, 0x2000
	s_cbranch_scc1 .Lmoe1_done
	s_barrier

; #define GEMM_WAITV(n) asm volatile("s_waitcnt vmcnt(" #n ")" ::: "memory")
; template <bool SWAP>
; __device__ __forceinline__ void gemm_main(f32x4 (&acc)[8][4], const TP& t, int nk, char* lds) {
;     ...
; #pragma unroll 1
;   for (int kt = 0; kt < nk - 3; ++kt) {
;     GEMM_WAITV(8);
;     GEMM_STEP(kt, true)
;   }
.Lmoe2_top:
	s_add_i32 s15, s14, 0xfffe8000
	s_and_b32 s15, s15, 0x18000
	v_add_u32_e32 v235, s15, v155
	v_add_u32_e32 v236, s15, v156
	ds_read_b128 v[178:181], v235
	ds_read_b128 v[158:161], v236 offset:16384
	ds_read_b128 v[162:165], v236 offset:17408
	ds_read_b128 v[170:173], v236 offset:18432
	ds_read_b128 v[174:177], v236 offset:19456
	ds_read_b128 v[182:185], v235 offset:1024
	ds_read_b128 v[186:189], v235 offset:2048
	ds_read_b128 v[190:193], v235 offset:3072
	s_and_b32 s99, s14, 0x18000
	s_add_i32 s99, s99, s98
	s_mov_b32 m0, s99
	v_lshl_add_u64 v[238:239], v[136:137], 0, s[18:19]
	global_load_lds_dwordx4 v[238:239], off
	s_add_i32 m0, s99, 0x400
	s_nop 0
	global_load_lds_dwordx4 v[136:137], off
	s_waitcnt lgkmcnt(0)
	s_barrier
	v_mfma_f32_16x16x32_bf16 v[124:127], v[158:161], v[178:181], v[124:127]
	v_mfma_f32_16x16x32_bf16 v[120:123], v[162:165], v[178:181], v[120:123]
	v_mfma_f32_16x16x32_bf16 v[116:119], v[170:173], v[178:181], v[116:119]
	v_mfma_f32_16x16x32_bf16 v[112:115], v[174:177], v[178:181], v[112:115]
	v_mfma_f32_16x16x32_bf16 v[108:111], v[158:161], v[182:185], v[108:111]
	v_mfma_f32_16x16x32_bf16 v[104:107], v[162:165], v[182:185], v[104:107]
	v_mfma_f32_16x16x32_bf16 v[100:103], v[170:173], v[182:185], v[100:103]
	v_mfma_f32_16x16x32_bf16 v[96:99], v[174:177], v[182:185], v[96:99]
	v_mfma_f32_16x16x32_bf16 v[92:95], v[158:161], v[186:189], v[92:95]
	v_mfma_f32_16x16x32_bf16 v[88:91], v[162:165], v[186:189], v[88:91]
	v_mfma_f32_16x16x32_bf16 v[84:87], v[170:173], v[186:189], v[84:87]
	v_mfma_f32_16x16x32_bf16 v[80:83], v[174:177], v[186:189], v[80:83]
	v_mfma_f32_16x16x32_bf16 v[76:79], v[158:161], v[190:193], v[76:79]
	v_mfma_f32_16x16x32_bf16 v[72:75], v[162:165], v[190:193], v[72:75]
	v_mfma_f32_16x16x32_bf16 v[68:71], v[170:173], v[190:193], v[68:71]
	v_mfma_f32_16x16x32_bf16 v[64:67], v[174:177], v[190:193], v[64:67]
	s_barrier
	ds_read_b128 v[178:181], v235 offset:4096
	ds_read_b128 v[182:185], v235 offset:5120
	ds_read_b128 v[186:189], v235 offset:6144
	ds_read_b128 v[190:193], v235 offset:7168
	s_add_i32 m0, s99, 0x4000
	s_nop 0
	global_load_lds_dwordx4 v[138:139], off
	s_add_i32 m0, s99, 0x4400
	s_nop 0
	global_load_lds_dwordx4 v[140:141], off
	v_lshl_add_u64 v[136:137], v[136:137], 0, 64
	v_lshl_add_u64 v[138:139], v[138:139], 0, 64
	v_lshl_add_u64 v[140:141], v[140:141], 0, 64
	s_add_i32 s14, s14, 0x8000
	s_waitcnt vmcnt(8)
	s_waitcnt lgkmcnt(0)
	s_barrier
	v_mfma_f32_16x16x32_bf16 v[60:63], v[158:161], v[178:181], v[60:63]
	v_mfma_f32_16x16x32_bf16 v[56:59], v[162:165], v[178:181], v[56:59]
	v_mfma_f32_16x16x32_bf16 v[52:55], v[170:173], v[178:181], v[52:55]
	v_mfma_f32_16x16x32_bf16 v[48:51], v[174:177], v[178:181], v[48:51]
	v_mfma_f32_16x16x32_bf16 v[44:47], v[158:161], v[182:185], v[44:47]
	v_mfma_f32_16x16x32_bf16 v[40:43], v[162:165], v[182:185], v[40:43]
	v_mfma_f32_16x16x32_bf16 v[36:39], v[170:173], v[182:185], v[36:39]
	v_mfma_f32_16x16x32_bf16 v[32:35], v[174:177], v[182:185], v[32:35]
	v_mfma_f32_16x16x32_bf16 v[28:31], v[158:161], v[186:189], v[28:31]
	v_mfma_f32_16x16x32_bf16 v[24:27], v[162:165], v[186:189], v[24:27]
	v_mfma_f32_16x16x32_bf16 v[20:23], v[170:173], v[186:189], v[20:23]
	v_mfma_f32_16x16x32_bf16 v[16:19], v[174:177], v[186:189], v[16:19]
	v_mfma_f32_16x16x32_bf16 v[12:15], v[158:161], v[190:193], v[12:15]
	v_mfma_f32_16x16x32_bf16 v[8:11], v[162:165], v[190:193], v[8:11]
	v_mfma_f32_16x16x32_bf16 v[4:7], v[170:173], v[190:193], v[4:7]
	v_mfma_f32_16x16x32_bf16 v[0:3], v[174:177], v[190:193], v[0:3]
	s_barrier
	s_cmp_lg_u32 s14, 0x2c0000
	s_cbranch_scc1 .Lmoe2_top
	v_add_u32_e32 v235, 0x8000, v155
	v_add_u32_e32 v236, 0x8000, v156
	ds_read_b128 v[178:181], v235
	ds_read_b128 v[158:161], v236 offset:16384
	ds_read_b128 v[162:165], v236 offset:17408
	ds_read_b128 v[170:173], v236 offset:18432
	ds_read_b128 v[174:177], v236 offset:19456
	ds_read_b128 v[182:185], v235 offset:1024
	ds_read_b128 v[186:189], v235 offset:2048
	ds_read_b128 v[190:193], v235 offset:3072
	s_waitcnt lgkmcnt(0)
	s_barrier
	v_mfma_f32_16x16x32_bf16 v[124:127], v[158:161], v[178:181], v[124:127]
	v_mfma_f32_16x16x32_bf16 v[120:123], v[162:165], v[178:181], v[120:123]
	v_mfma_f32_16x16x32_bf16 v[116:119], v[170:173], v[178:181], v[116:119]
	v_mfma_f32_16x16x32_bf16 v[112:115], v[174:177], v[178:181], v[112:115]
	v_mfma_f32_16x16x32_bf16 v[108:111], v[158:161], v[182:185], v[108:111]
	v_mfma_f32_16x16x32_bf16 v[104:107], v[162:165], v[182:185], v[104:107]
	v_mfma_f32_16x16x32_bf16 v[100:103], v[170:173], v[182:185], v[100:103]
	v_mfma_f32_16x16x32_bf16 v[96:99], v[174:177], v[182:185], v[96:99]
	v_mfma_f32_16x16x32_bf16 v[92:95], v[158:161], v[186:189], v[92:95]
	v_mfma_f32_16x16x32_bf16 v[88:91], v[162:165], v[186:189], v[88:91]
	v_mfma_f32_16x16x32_bf16 v[84:87], v[170:173], v[186:189], v[84:87]
	v_mfma_f32_16x16x32_bf16 v[80:83], v[174:177], v[186:189], v[80:83]
	v_mfma_f32_16x16x32_bf16 v[76:79], v[158:161], v[190:193], v[76:79]
	v_mfma_f32_16x16x32_bf16 v[72:75], v[162:165], v[190:193], v[72:75]
	v_mfma_f32_16x16x32_bf16 v[68:71], v[170:173], v[190:193], v[68:71]
	v_mfma_f32_16x16x32_bf16 v[64:67], v[174:177], v[190:193], v[64:67]
	s_barrier
	ds_read_b128 v[178:181], v235 offset:4096
	ds_read_b128 v[182:185], v235 offset:5120
	ds_read_b128 v[186:189], v235 offset:6144
	ds_read_b128 v[190:193], v235 offset:7168
	s_waitcnt vmcnt(4)
	s_waitcnt lgkmcnt(0)
	s_barrier
; #define GEMM_WAITV(n) asm volatile("s_waitcnt vmcnt(" #n ")" ::: "memory")
; template <bool SWAP>
; __device__ __forceinline__ void gemm_main(f32x4 (&acc)[8][4], const TP& t, int nk, char* lds) {
;     ...
; #pragma unroll 1
;   for (int kt = nk - 3; kt < nk; ++kt) {
;     const int rem = nk - kt;
;     if (rem == 3) GEMM_WAITV(8); else if (rem == 2) GEMM_WAITV(4); else GEMM_WAITV(0);
;     GEMM_STEP(kt, false)
;   }
;   __builtin_amdgcn_s_barrier();
	v_mfma_f32_16x16x32_bf16 v[60:63], v[158:161], v[178:181], v[60:63]
	v_mfma_f32_16x16x32_bf16 v[56:59], v[162:165], v[178:181], v[56:59]
	v_mfma_f32_16x16x32_bf16 v[52:55], v[170:173], v[178:181], v[52:55]
	v_mfma_f32_16x16x32_bf16 v[48:51], v[174:177], v[178:181], v[48:51]
	v_mfma_f32_16x16x32_bf16 v[44:47], v[158:161], v[182:185], v[44:47]
	v_mfma_f32_16x16x32_bf16 v[40:43], v[162:165], v[182:185], v[40:43]
	v_mfma_f32_16x16x32_bf16 v[36:39], v[170:173], v[182:185], v[36:39]
	v_mfma_f32_16x16x32_bf16 v[32:35], v[174:177], v[182:185], v[32:35]
	v_mfma_f32_16x16x32_bf16 v[28:31], v[158:161], v[186:189], v[28:31]
	v_mfma_f32_16x16x32_bf16 v[24:27], v[162:165], v[186:189], v[24:27]
	v_mfma_f32_16x16x32_bf16 v[20:23], v[170:173], v[186:189], v[20:23]
	v_mfma_f32_16x16x32_bf16 v[16:19], v[174:177], v[186:189], v[16:19]
	v_mfma_f32_16x16x32_bf16 v[12:15], v[158:161], v[190:193], v[12:15]
	v_mfma_f32_16x16x32_bf16 v[8:11], v[162:165], v[190:193], v[8:11]
	v_mfma_f32_16x16x32_bf16 v[4:7], v[170:173], v[190:193], v[4:7]
	v_mfma_f32_16x16x32_bf16 v[0:3], v[174:177], v[190:193], v[0:3]
	s_barrier
	v_add_u32_e32 v235, 0x10000, v155
	v_add_u32_e32 v236, 0x10000, v156
	ds_read_b128 v[178:181], v235
	ds_read_b128 v[158:161], v236 offset:16384
	ds_read_b128 v[162:165], v236 offset:17408
	ds_read_b128 v[170:173], v236 offset:18432
	ds_read_b128 v[174:177], v236 offset:19456
	ds_read_b128 v[182:185], v235 offset:1024
	ds_read_b128 v[186:189], v235 offset:2048
	ds_read_b128 v[190:193], v235 offset:3072
	s_waitcnt lgkmcnt(0)
	s_barrier
	v_mfma_f32_16x16x32_bf16 v[124:127], v[158:161], v[178:181], v[124:127]
	v_mfma_f32_16x16x32_bf16 v[120:123], v[162:165], v[178:181], v[120:123]
	v_mfma_f32_16x16x32_bf16 v[116:119], v[170:173], v[178:181], v[116:119]
	v_mfma_f32_16x16x32_bf16 v[112:115], v[174:177], v[178:181], v[112:115]
	v_mfma_f32_16x16x32_bf16 v[108:111], v[158:161], v[182:185], v[108:111]
	v_mfma_f32_16x16x32_bf16 v[104:107], v[162:165], v[182:185], v[104:107]
	v_mfma_f32_16x16x32_bf16 v[100:103], v[170:173], v[182:185], v[100:103]
	v_mfma_f32_16x16x32_bf16 v[96:99], v[174:177], v[182:185], v[96:99]
	v_mfma_f32_16x16x32_bf16 v[92:95], v[158:161], v[186:189], v[92:95]
	v_mfma_f32_16x16x32_bf16 v[88:91], v[162:165], v[186:189], v[88:91]
	v_mfma_f32_16x16x32_bf16 v[84:87], v[170:173], v[186:189], v[84:87]
	v_mfma_f32_16x16x32_bf16 v[80:83], v[174:177], v[186:189], v[80:83]
	v_mfma_f32_16x16x32_bf16 v[76:79], v[158:161], v[190:193], v[76:79]
	v_mfma_f32_16x16x32_bf16 v[72:75], v[162:165], v[190:193], v[72:75]
	v_mfma_f32_16x16x32_bf16 v[68:71], v[170:173], v[190:193], v[68:71]
	v_mfma_f32_16x16x32_bf16 v[64:67], v[174:177], v[190:193], v[64:67]
	s_barrier
	ds_read_b128 v[178:181], v235 offset:4096
	ds_read_b128 v[182:185], v235 offset:5120
	ds_read_b128 v[186:189], v235 offset:6144
	ds_read_b128 v[190:193], v235 offset:7168
	s_waitcnt vmcnt(0)
	s_waitcnt lgkmcnt(0)
	s_barrier
	v_mfma_f32_16x16x32_bf16 v[60:63], v[158:161], v[178:181], v[60:63]
	v_mfma_f32_16x16x32_bf16 v[56:59], v[162:165], v[178:181], v[56:59]
	v_mfma_f32_16x16x32_bf16 v[52:55], v[170:173], v[178:181], v[52:55]
	v_mfma_f32_16x16x32_bf16 v[48:51], v[174:177], v[178:181], v[48:51]
	v_mfma_f32_16x16x32_bf16 v[44:47], v[158:161], v[182:185], v[44:47]
	v_mfma_f32_16x16x32_bf16 v[40:43], v[162:165], v[182:185], v[40:43]
	v_mfma_f32_16x16x32_bf16 v[36:39], v[170:173], v[182:185], v[36:39]
	v_mfma_f32_16x16x32_bf16 v[32:35], v[174:177], v[182:185], v[32:35]
	v_mfma_f32_16x16x32_bf16 v[28:31], v[158:161], v[186:189], v[28:31]
	v_mfma_f32_16x16x32_bf16 v[24:27], v[162:165], v[186:189], v[24:27]
	v_mfma_f32_16x16x32_bf16 v[20:23], v[170:173], v[186:189], v[20:23]
	v_mfma_f32_16x16x32_bf16 v[16:19], v[174:177], v[186:189], v[16:19]
	v_mfma_f32_16x16x32_bf16 v[12:15], v[158:161], v[190:193], v[12:15]
	v_mfma_f32_16x16x32_bf16 v[8:11], v[162:165], v[190:193], v[8:11]
	v_mfma_f32_16x16x32_bf16 v[4:7], v[170:173], v[190:193], v[4:7]
	v_mfma_f32_16x16x32_bf16 v[0:3], v[174:177], v[190:193], v[0:3]
	s_barrier
	v_add_u32_e32 v235, 0x18000, v155
	v_add_u32_e32 v236, 0x18000, v156
	ds_read_b128 v[178:181], v235
	ds_read_b128 v[158:161], v236 offset:16384
	ds_read_b128 v[162:165], v236 offset:17408
	ds_read_b128 v[170:173], v236 offset:18432
	ds_read_b128 v[174:177], v236 offset:19456
	ds_read_b128 v[182:185], v235 offset:1024
	ds_read_b128 v[186:189], v235 offset:2048
	ds_read_b128 v[190:193], v235 offset:3072
	s_waitcnt lgkmcnt(0)
	s_barrier
	v_mfma_f32_16x16x32_bf16 v[124:127], v[158:161], v[178:181], v[124:127]
	v_mfma_f32_16x16x32_bf16 v[120:123], v[162:165], v[178:181], v[120:123]
	v_mfma_f32_16x16x32_bf16 v[116:119], v[170:173], v[178:181], v[116:119]
	v_mfma_f32_16x16x32_bf16 v[112:115], v[174:177], v[178:181], v[112:115]
	v_mfma_f32_16x16x32_bf16 v[108:111], v[158:161], v[182:185], v[108:111]
	v_mfma_f32_16x16x32_bf16 v[104:107], v[162:165], v[182:185], v[104:107]
	v_mfma_f32_16x16x32_bf16 v[100:103], v[170:173], v[182:185], v[100:103]
	v_mfma_f32_16x16x32_bf16 v[96:99], v[174:177], v[182:185], v[96:99]
	v_mfma_f32_16x16x32_bf16 v[92:95], v[158:161], v[186:189], v[92:95]
	v_mfma_f32_16x16x32_bf16 v[88:91], v[162:165], v[186:189], v[88:91]
	v_mfma_f32_16x16x32_bf16 v[84:87], v[170:173], v[186:189], v[84:87]
	v_mfma_f32_16x16x32_bf16 v[80:83], v[174:177], v[186:189], v[80:83]
	v_mfma_f32_16x16x32_bf16 v[76:79], v[158:161], v[190:193], v[76:79]
	v_mfma_f32_16x16x32_bf16 v[72:75], v[162:165], v[190:193], v[72:75]
	v_mfma_f32_16x16x32_bf16 v[68:71], v[170:173], v[190:193], v[68:71]
	v_mfma_f32_16x16x32_bf16 v[64:67], v[174:177], v[190:193], v[64:67]
	s_barrier
	ds_read_b128 v[178:181], v235 offset:4096
	ds_read_b128 v[182:185], v235 offset:5120
	ds_read_b128 v[186:189], v235 offset:6144
	ds_read_b128 v[190:193], v235 offset:7168
	s_waitcnt lgkmcnt(0)
	s_barrier
	v_mfma_f32_16x16x32_bf16 v[60:63], v[158:161], v[178:181], v[60:63]
	v_mfma_f32_16x16x32_bf16 v[56:59], v[162:165], v[178:181], v[56:59]
	v_mfma_f32_16x16x32_bf16 v[52:55], v[170:173], v[178:181], v[52:55]
	v_mfma_f32_16x16x32_bf16 v[48:51], v[174:177], v[178:181], v[48:51]
	v_mfma_f32_16x16x32_bf16 v[44:47], v[158:161], v[182:185], v[44:47]
	v_mfma_f32_16x16x32_bf16 v[40:43], v[162:165], v[182:185], v[40:43]
	v_mfma_f32_16x16x32_bf16 v[36:39], v[170:173], v[182:185], v[36:39]
	v_mfma_f32_16x16x32_bf16 v[32:35], v[174:177], v[182:185], v[32:35]
	v_mfma_f32_16x16x32_bf16 v[28:31], v[158:161], v[186:189], v[28:31]
	v_mfma_f32_16x16x32_bf16 v[24:27], v[162:165], v[186:189], v[24:27]
	v_mfma_f32_16x16x32_bf16 v[20:23], v[170:173], v[186:189], v[20:23]
	v_mfma_f32_16x16x32_bf16 v[16:19], v[174:177], v[186:189], v[16:19]
	v_mfma_f32_16x16x32_bf16 v[12:15], v[158:161], v[190:193], v[12:15]
	v_mfma_f32_16x16x32_bf16 v[8:11], v[162:165], v[190:193], v[8:11]
	v_mfma_f32_16x16x32_bf16 v[4:7], v[170:173], v[190:193], v[4:7]
	v_mfma_f32_16x16x32_bf16 v[0:3], v[174:177], v[190:193], v[0:3]
	s_barrier
	s_cmp_ge_u32 s98, 0x2000
	s_cbranch_scc1 .Lmoe2_done
	s_barrier
